# loop-edge: K-loop counter and pointer increments and the exit compare moved from behind the closing barrier into the MFMA shadow of the last super-phase
# speedup vs baseline: 1.0086x; 1.0022x over previous
.LBB0_1891:
	v_add_u32_e32 v2, s83, v189
	ds_read_b128 v[28:31], v2
	ds_read_b128 v[32:35], v2 offset:16
	ds_read_b128 v[20:23], v2 offset:2048
	ds_read_b128 v[24:27], v2 offset:2064
	v_add_u32_e32 v2, s44, v189
	ds_read_b128 v[12:15], v2
	ds_read_b128 v[16:19], v2 offset:16
	ds_read_b128 v[4:7], v2 offset:2048
	ds_read_b128 v[8:11], v2 offset:2064
	s_add_u32 s10, s8, 0xfffc0080
	s_addc_u32 s11, s9, -1
	s_cmp_eq_u32 s25, 12
	s_cselect_b32 s13, s3, s11
	s_cselect_b32 s12, s14, s10
	s_cselect_b32 s11, s15, s24
	s_cselect_b32 s10, s18, s19
	v_lshl_add_u64 v[208:209], s[8:9], 0, v[172:173]
	s_add_i32 m0, s16, 0xc000
	ds_read_b128 v[176:179], v191
	ds_read_b128 v[180:183], v191 offset:16
	ds_read_b128 v[192:195], v191 offset:2048
	ds_read_b128 v[196:199], v191 offset:2064
	ds_read_b128 v[200:203], v191 offset:4096
	ds_read_b128 v[204:207], v191 offset:4112
	ds_read_b128 v[216:219], v191 offset:6144
	ds_read_b128 v[220:223], v191 offset:6160
	global_load_lds_dwordx4 v[208:209], off
	v_lshl_add_u64 v[208:209], s[8:9], 0, v[174:175]
	s_add_i32 m0, s16, 0xe000
	s_nop 0
	global_load_lds_dwordx4 v[208:209], off
	s_waitcnt vmcnt(8)
	s_waitcnt lgkmcnt(0)
	s_barrier
	s_setprio 1
	s_waitcnt lgkmcnt(0)
	v_mfma_scale_f32_16x16x128_f8f6f4 v[160:163], v[28:35], v[176:183], v[160:163], v187, v185 op_sel_hi:[0,0,0]
	v_mfma_scale_f32_16x16x128_f8f6f4 v[156:159], v[20:27], v[176:183], v[156:159], v187, v185 op_sel_hi:[0,0,0]
	v_mfma_scale_f32_16x16x128_f8f6f4 v[144:147], v[28:35], v[192:199], v[144:147], v187, v185 op_sel_hi:[0,0,0]
	v_mfma_scale_f32_16x16x128_f8f6f4 v[140:143], v[20:27], v[192:199], v[140:143], v187, v185 op_sel_hi:[0,0,0]
	v_mfma_scale_f32_16x16x128_f8f6f4 v[128:131], v[28:35], v[200:207], v[128:131], v187, v185 op_sel_hi:[0,0,0]
	v_mfma_scale_f32_16x16x128_f8f6f4 v[124:127], v[20:27], v[200:207], v[124:127], v187, v185 op_sel_hi:[0,0,0]
	v_mfma_scale_f32_16x16x128_f8f6f4 v[112:115], v[28:35], v[216:223], v[112:115], v187, v185 op_sel_hi:[0,0,0]
	v_mfma_scale_f32_16x16x128_f8f6f4 v[108:111], v[20:27], v[216:223], v[108:111], v187, v185 op_sel_hi:[0,0,0]
	s_setprio 0
	s_setprio 1
	v_mfma_scale_f32_16x16x128_f8f6f4 v[152:155], v[12:19], v[176:183], v[152:155], v187, v185 op_sel_hi:[0,0,0]
	v_mfma_scale_f32_16x16x128_f8f6f4 v[148:151], v[4:11], v[176:183], v[148:151], v187, v185 op_sel_hi:[0,0,0]
	v_mfma_scale_f32_16x16x128_f8f6f4 v[136:139], v[12:19], v[192:199], v[136:139], v187, v185 op_sel_hi:[0,0,0]
	v_mfma_scale_f32_16x16x128_f8f6f4 v[132:135], v[4:11], v[192:199], v[132:135], v187, v185 op_sel_hi:[0,0,0]
	v_mfma_scale_f32_16x16x128_f8f6f4 v[120:123], v[12:19], v[200:207], v[120:123], v187, v185 op_sel_hi:[0,0,0]
	v_mfma_scale_f32_16x16x128_f8f6f4 v[116:119], v[4:11], v[200:207], v[116:119], v187, v185 op_sel_hi:[0,0,0]
	v_mfma_scale_f32_16x16x128_f8f6f4 v[104:107], v[12:19], v[216:223], v[104:107], v187, v185 op_sel_hi:[0,0,0]
	v_mfma_scale_f32_16x16x128_f8f6f4 v[100:103], v[4:11], v[216:223], v[100:103], v187, v185 op_sel_hi:[0,0,0]
	s_setprio 0
	s_barrier
	s_mov_b32 m0, s22
	v_lshl_add_u64 v[176:177], s[10:11], 0, v[166:167]
	s_add_u32 s56, s10, 0x40000
	ds_read_b128 v[192:195], v191 offset:16384
	ds_read_b128 v[196:199], v191 offset:16400
	ds_read_b128 v[200:203], v191 offset:18432
	ds_read_b128 v[204:207], v191 offset:18448
	ds_read_b128 v[216:219], v191 offset:20480
	ds_read_b128 v[220:223], v191 offset:20496
	ds_read_b128 v[224:227], v191 offset:22528
	ds_read_b128 v[228:231], v191 offset:22544
	global_load_lds_dwordx4 v[176:177], off
	v_lshl_add_u64 v[178:179], s[10:11], 0, v[170:171]
	s_mov_b32 m0, s23
	s_addc_u32 s57, s11, 0
	global_load_lds_dwordx4 v[178:179], off
	v_lshl_add_u64 v[180:181], s[56:57], 0, v[166:167]
	s_mov_b32 m0, s75
	v_lshl_add_u64 v[182:183], s[12:13], 0, v[168:169]
	global_load_lds_dwordx4 v[180:181], off
	v_lshl_add_u64 v[180:181], s[56:57], 0, v[170:171]
	s_mov_b32 m0, s37
	s_nop 0
	global_load_lds_dwordx4 v[180:181], off
	v_lshl_add_u64 v[180:181], s[12:13], 0, v[164:165]
	s_mov_b32 m0, s16
	s_nop 0
	global_load_lds_dwordx4 v[180:181], off
	s_mov_b32 m0, s73
	s_nop 0
	global_load_lds_dwordx4 v[182:183], off
	s_waitcnt vmcnt(8)
	s_waitcnt lgkmcnt(0)
	s_barrier
	s_setprio 1
	s_waitcnt lgkmcnt(0)
	v_mfma_scale_f32_16x16x128_f8f6f4 v[96:99], v[28:35], v[192:199], v[96:99], v187, v185 op_sel_hi:[0,0,0]
	v_mfma_scale_f32_16x16x128_f8f6f4 v[92:95], v[20:27], v[192:199], v[92:95], v187, v185 op_sel_hi:[0,0,0]
	v_mfma_scale_f32_16x16x128_f8f6f4 v[80:83], v[28:35], v[200:207], v[80:83], v187, v185 op_sel_hi:[0,0,0]
	v_mfma_scale_f32_16x16x128_f8f6f4 v[76:79], v[20:27], v[200:207], v[76:79], v187, v185 op_sel_hi:[0,0,0]
	v_mfma_scale_f32_16x16x128_f8f6f4 v[64:67], v[28:35], v[216:223], v[64:67], v187, v185 op_sel_hi:[0,0,0]
	v_mfma_scale_f32_16x16x128_f8f6f4 v[60:63], v[20:27], v[216:223], v[60:63], v187, v185 op_sel_hi:[0,0,0]
	v_mfma_scale_f32_16x16x128_f8f6f4 v[48:51], v[28:35], v[224:231], v[48:51], v187, v185 op_sel_hi:[0,0,0]
	v_mfma_scale_f32_16x16x128_f8f6f4 v[44:47], v[20:27], v[224:231], v[44:47], v187, v185 op_sel_hi:[0,0,0]
	s_setprio 0
	s_setprio 1
	v_mfma_scale_f32_16x16x128_f8f6f4 v[88:91], v[12:19], v[192:199], v[88:91], v187, v185 op_sel_hi:[0,0,0]
	v_mfma_scale_f32_16x16x128_f8f6f4 v[84:87], v[4:11], v[192:199], v[84:87], v187, v185 op_sel_hi:[0,0,0]
	v_mfma_scale_f32_16x16x128_f8f6f4 v[72:75], v[12:19], v[200:207], v[72:75], v187, v185 op_sel_hi:[0,0,0]
	v_mfma_scale_f32_16x16x128_f8f6f4 v[68:71], v[4:11], v[200:207], v[68:71], v187, v185 op_sel_hi:[0,0,0]
	v_mfma_scale_f32_16x16x128_f8f6f4 v[56:59], v[12:19], v[216:223], v[56:59], v187, v185 op_sel_hi:[0,0,0]
	v_mfma_scale_f32_16x16x128_f8f6f4 v[52:55], v[4:11], v[216:223], v[52:55], v187, v185 op_sel_hi:[0,0,0]
	v_mfma_scale_f32_16x16x128_f8f6f4 v[40:43], v[12:19], v[224:231], v[40:43], v187, v185 op_sel_hi:[0,0,0]
	v_mfma_scale_f32_16x16x128_f8f6f4 v[36:39], v[4:11], v[224:231], v[36:39], v187, v185 op_sel_hi:[0,0,0]
	s_setprio 0
	s_barrier
	v_add_u32_e32 v2, s45, v189
	ds_read_b128 v[28:31], v2
	ds_read_b128 v[32:35], v2 offset:16
	ds_read_b128 v[20:23], v2 offset:2048
	ds_read_b128 v[24:27], v2 offset:2064
	v_add_u32_e32 v2, s74, v189
	ds_read_b128 v[12:15], v2
	ds_read_b128 v[16:19], v2 offset:16
	ds_read_b128 v[4:7], v2 offset:2048
	ds_read_b128 v[8:11], v2 offset:2064
	s_add_u32 s12, s12, 0x40000
	s_addc_u32 s13, s13, 0
	s_mov_b32 m0, s82
	v_lshl_add_u64 v[208:209], s[12:13], 0, v[164:165]
	ds_read_b128 v[192:195], v191 offset:32768
	ds_read_b128 v[196:199], v191 offset:32784
	ds_read_b128 v[200:203], v191 offset:34816
	ds_read_b128 v[204:207], v191 offset:34832
	ds_read_b128 v[216:219], v191 offset:36864
	ds_read_b128 v[220:223], v191 offset:36880
	ds_read_b128 v[224:227], v191 offset:38912
	ds_read_b128 v[228:231], v191 offset:38928
	global_load_lds_dwordx4 v[208:209], off
	v_lshl_add_u64 v[208:209], s[12:13], 0, v[168:169]
	s_mov_b32 m0, s40
	s_nop 0
	global_load_lds_dwordx4 v[208:209], off
	s_waitcnt vmcnt(8)
	s_waitcnt lgkmcnt(0)
	s_barrier
	s_setprio 1
	s_waitcnt lgkmcnt(0)
	v_mfma_scale_f32_16x16x128_f8f6f4 v[160:163], v[28:35], v[192:199], v[160:163], v187, v185 op_sel_hi:[0,0,0]
	v_mfma_scale_f32_16x16x128_f8f6f4 v[156:159], v[20:27], v[192:199], v[156:159], v187, v185 op_sel_hi:[0,0,0]
	v_mfma_scale_f32_16x16x128_f8f6f4 v[144:147], v[28:35], v[200:207], v[144:147], v187, v185 op_sel_hi:[0,0,0]
	v_mfma_scale_f32_16x16x128_f8f6f4 v[140:143], v[20:27], v[200:207], v[140:143], v187, v185 op_sel_hi:[0,0,0]
	v_mfma_scale_f32_16x16x128_f8f6f4 v[128:131], v[28:35], v[216:223], v[128:131], v187, v185 op_sel_hi:[0,0,0]
	v_mfma_scale_f32_16x16x128_f8f6f4 v[124:127], v[20:27], v[216:223], v[124:127], v187, v185 op_sel_hi:[0,0,0]
	v_mfma_scale_f32_16x16x128_f8f6f4 v[112:115], v[28:35], v[224:231], v[112:115], v187, v185 op_sel_hi:[0,0,0]
	v_mfma_scale_f32_16x16x128_f8f6f4 v[108:111], v[20:27], v[224:231], v[108:111], v187, v185 op_sel_hi:[0,0,0]
	s_setprio 0
	s_setprio 1
	v_mfma_scale_f32_16x16x128_f8f6f4 v[152:155], v[12:19], v[192:199], v[152:155], v187, v185 op_sel_hi:[0,0,0]
	v_mfma_scale_f32_16x16x128_f8f6f4 v[148:151], v[4:11], v[192:199], v[148:151], v187, v185 op_sel_hi:[0,0,0]
	v_mfma_scale_f32_16x16x128_f8f6f4 v[136:139], v[12:19], v[200:207], v[136:139], v187, v185 op_sel_hi:[0,0,0]
	v_mfma_scale_f32_16x16x128_f8f6f4 v[132:135], v[4:11], v[200:207], v[132:135], v187, v185 op_sel_hi:[0,0,0]
	v_mfma_scale_f32_16x16x128_f8f6f4 v[120:123], v[12:19], v[216:223], v[120:123], v187, v185 op_sel_hi:[0,0,0]
	v_mfma_scale_f32_16x16x128_f8f6f4 v[116:119], v[4:11], v[216:223], v[116:119], v187, v185 op_sel_hi:[0,0,0]
	v_mfma_scale_f32_16x16x128_f8f6f4 v[104:107], v[12:19], v[224:231], v[104:107], v187, v185 op_sel_hi:[0,0,0]
	v_mfma_scale_f32_16x16x128_f8f6f4 v[100:103], v[4:11], v[224:231], v[100:103], v187, v185 op_sel_hi:[0,0,0]
	s_setprio 0
	s_barrier
	s_mov_b32 m0, s49
	v_lshl_add_u64 v[176:177], v[176:177], 0, s[64:65]
	s_add_u32 s10, s10, 0x40080
	ds_read_b128 v[192:195], v191 offset:49152
	ds_read_b128 v[196:199], v191 offset:49168
	ds_read_b128 v[200:203], v191 offset:51200
	ds_read_b128 v[204:207], v191 offset:51216
	ds_read_b128 v[216:219], v191 offset:53248
	ds_read_b128 v[220:223], v191 offset:53264
	ds_read_b128 v[224:227], v191 offset:55296
	ds_read_b128 v[228:231], v191 offset:55312
	global_load_lds_dwordx4 v[176:177], off
	v_lshl_add_u64 v[176:177], v[178:179], 0, s[64:65]
	s_mov_b32 m0, s84
	s_addc_u32 s11, s11, 0
	global_load_lds_dwordx4 v[176:177], off
	v_lshl_add_u64 v[176:177], s[10:11], 0, v[166:167]
	s_mov_b32 m0, s27
	s_nop 0
	global_load_lds_dwordx4 v[176:177], off
	v_lshl_add_u64 v[176:177], s[10:11], 0, v[170:171]
	s_mov_b32 m0, s48
	s_nop 0
	global_load_lds_dwordx4 v[176:177], off
	v_lshl_add_u64 v[176:177], v[180:181], 0, s[64:65]
	s_mov_b32 m0, s85
	s_nop 0
	global_load_lds_dwordx4 v[176:177], off
	v_lshl_add_u64 v[176:177], v[182:183], 0, s[64:65]
	s_mov_b32 m0, s26
	s_nop 0
	global_load_lds_dwordx4 v[176:177], off
	s_waitcnt vmcnt(8)
	s_waitcnt lgkmcnt(0)
	s_barrier
	s_setprio 1
	s_waitcnt lgkmcnt(0)
	v_mfma_scale_f32_16x16x128_f8f6f4 v[96:99], v[28:35], v[192:199], v[96:99], v187, v185 op_sel_hi:[0,0,0]
	v_mfma_scale_f32_16x16x128_f8f6f4 v[92:95], v[20:27], v[192:199], v[92:95], v187, v185 op_sel_hi:[0,0,0]
	v_mfma_scale_f32_16x16x128_f8f6f4 v[80:83], v[28:35], v[200:207], v[80:83], v187, v185 op_sel_hi:[0,0,0]
	v_mfma_scale_f32_16x16x128_f8f6f4 v[76:79], v[20:27], v[200:207], v[76:79], v187, v185 op_sel_hi:[0,0,0]
	v_mfma_scale_f32_16x16x128_f8f6f4 v[64:67], v[28:35], v[216:223], v[64:67], v187, v185 op_sel_hi:[0,0,0]
	v_mfma_scale_f32_16x16x128_f8f6f4 v[60:63], v[20:27], v[216:223], v[60:63], v187, v185 op_sel_hi:[0,0,0]
	v_mfma_scale_f32_16x16x128_f8f6f4 v[48:51], v[28:35], v[224:231], v[48:51], v187, v185 op_sel_hi:[0,0,0]
	v_mfma_scale_f32_16x16x128_f8f6f4 v[44:47], v[20:27], v[224:231], v[44:47], v187, v185 op_sel_hi:[0,0,0]
	s_setprio 0
	s_setprio 1
	v_mfma_scale_f32_16x16x128_f8f6f4 v[88:91], v[12:19], v[192:199], v[88:91], v187, v185 op_sel_hi:[0,0,0]
	v_mfma_scale_f32_16x16x128_f8f6f4 v[84:87], v[4:11], v[192:199], v[84:87], v187, v185 op_sel_hi:[0,0,0]
	v_mfma_scale_f32_16x16x128_f8f6f4 v[72:75], v[12:19], v[200:207], v[72:75], v187, v185 op_sel_hi:[0,0,0]
	v_mfma_scale_f32_16x16x128_f8f6f4 v[68:71], v[4:11], v[200:207], v[68:71], v187, v185 op_sel_hi:[0,0,0]
	s_add_i32 s25, s25, 2
	v_mfma_scale_f32_16x16x128_f8f6f4 v[56:59], v[12:19], v[216:223], v[56:59], v187, v185 op_sel_hi:[0,0,0]
	s_add_u32 s8, s8, 0x100
	s_addc_u32 s9, s9, 0
	v_mfma_scale_f32_16x16x128_f8f6f4 v[52:55], v[4:11], v[216:223], v[52:55], v187, v185 op_sel_hi:[0,0,0]
	s_add_u32 s19, s19, 0x100
	s_addc_u32 s24, s24, 0
	v_mfma_scale_f32_16x16x128_f8f6f4 v[40:43], v[12:19], v[224:231], v[40:43], v187, v185 op_sel_hi:[0,0,0]
	s_cmp_gt_u32 s25, 13
	v_mfma_scale_f32_16x16x128_f8f6f4 v[36:39], v[4:11], v[224:231], v[36:39], v187, v185 op_sel_hi:[0,0,0]
	s_setprio 0
	s_barrier
	s_cbranch_scc0 .LBB0_1891
	v_readlane_b32 s8, v255, 13
	v_readlane_b32 s9, v255, 14
	s_and_b64 vcc, exec, s[8:9]
	s_cbranch_vccz .LBB0_1894
	s_barrier

.LBB0_2890:
	v_add_u32_e32 v4, s18, v184
	v_add_u32_e32 v8, s19, v184
	s_add_u32 s14, s48, s12
	ds_read_b128 v[28:31], v4
	ds_read_b128 v[32:35], v4 offset:16
	ds_read_b128 v[20:23], v4 offset:2048
	ds_read_b128 v[24:27], v4 offset:2064
	ds_read_b128 v[12:15], v8
	ds_read_b128 v[16:19], v8 offset:16
	ds_read_b128 v[4:7], v8 offset:2048
	ds_read_b128 v[8:11], v8 offset:2064
	s_addc_u32 s15, s49, s13
	s_add_u32 s14, s14, 0x45c00100
	s_addc_u32 s15, s15, 0
	s_add_u32 s53, s50, s12
	s_addc_u32 s56, s51, s13
	s_cmpk_eq_i32 s12, 0x700
	s_cselect_b32 s25, s11, s15
	s_cselect_b32 s24, s10, s14
	s_cselect_b32 s15, s3, s56
	s_cselect_b32 s14, s2, s53
	v_lshl_add_u64 v[210:211], v[170:171], 0, s[12:13]
	s_add_i32 m0, s37, 0xc000
	ds_read_b128 v[174:177], v185
	ds_read_b128 v[178:181], v185 offset:16
	ds_read_b128 v[186:189], v185 offset:2048
	ds_read_b128 v[190:193], v185 offset:2064
	ds_read_b128 v[194:197], v185 offset:4096
	ds_read_b128 v[198:201], v185 offset:4112
	ds_read_b128 v[202:205], v185 offset:6144
	ds_read_b128 v[206:209], v185 offset:6160
	global_load_lds_dwordx4 v[210:211], off
	v_lshl_add_u64 v[210:211], v[172:173], 0, s[12:13]
	s_add_i32 m0, s37, 0xe000
	s_nop 0
	global_load_lds_dwordx4 v[210:211], off
	s_waitcnt vmcnt(8)
	s_waitcnt lgkmcnt(0)
	s_barrier
	s_setprio 1
	s_waitcnt lgkmcnt(0)
	v_mfma_scale_f32_16x16x128_f8f6f4 v[160:163], v[28:35], v[174:181], v[160:163], v183, v182 op_sel_hi:[0,0,0]
	v_mfma_scale_f32_16x16x128_f8f6f4 v[156:159], v[20:27], v[174:181], v[156:159], v183, v182 op_sel_hi:[0,0,0]
	v_mfma_scale_f32_16x16x128_f8f6f4 v[144:147], v[28:35], v[186:193], v[144:147], v183, v182 op_sel_hi:[0,0,0]
	v_mfma_scale_f32_16x16x128_f8f6f4 v[140:143], v[20:27], v[186:193], v[140:143], v183, v182 op_sel_hi:[0,0,0]
	v_mfma_scale_f32_16x16x128_f8f6f4 v[128:131], v[28:35], v[194:201], v[128:131], v183, v182 op_sel_hi:[0,0,0]
	v_mfma_scale_f32_16x16x128_f8f6f4 v[124:127], v[20:27], v[194:201], v[124:127], v183, v182 op_sel_hi:[0,0,0]
	v_mfma_scale_f32_16x16x128_f8f6f4 v[112:115], v[28:35], v[202:209], v[112:115], v183, v182 op_sel_hi:[0,0,0]
	v_mfma_scale_f32_16x16x128_f8f6f4 v[108:111], v[20:27], v[202:209], v[108:111], v183, v182 op_sel_hi:[0,0,0]
	s_setprio 0
	s_setprio 1
	v_mfma_scale_f32_16x16x128_f8f6f4 v[152:155], v[12:19], v[174:181], v[152:155], v183, v182 op_sel_hi:[0,0,0]
	v_mfma_scale_f32_16x16x128_f8f6f4 v[148:151], v[4:11], v[174:181], v[148:151], v183, v182 op_sel_hi:[0,0,0]
	v_mfma_scale_f32_16x16x128_f8f6f4 v[136:139], v[12:19], v[186:193], v[136:139], v183, v182 op_sel_hi:[0,0,0]
	v_mfma_scale_f32_16x16x128_f8f6f4 v[132:135], v[4:11], v[186:193], v[132:135], v183, v182 op_sel_hi:[0,0,0]
	v_mfma_scale_f32_16x16x128_f8f6f4 v[120:123], v[12:19], v[194:201], v[120:123], v183, v182 op_sel_hi:[0,0,0]
	v_mfma_scale_f32_16x16x128_f8f6f4 v[116:119], v[4:11], v[194:201], v[116:119], v183, v182 op_sel_hi:[0,0,0]
	v_mfma_scale_f32_16x16x128_f8f6f4 v[104:107], v[12:19], v[202:209], v[104:107], v183, v182 op_sel_hi:[0,0,0]
	v_mfma_scale_f32_16x16x128_f8f6f4 v[100:103], v[4:11], v[202:209], v[100:103], v183, v182 op_sel_hi:[0,0,0]
	s_setprio 0
	s_barrier
	s_mov_b32 m0, s23
	v_lshl_add_u64 v[174:175], s[14:15], 0, v[2:3]
	s_add_u32 s56, s14, 0x40000
	ds_read_b128 v[186:189], v185 offset:16384
	ds_read_b128 v[190:193], v185 offset:16400
	ds_read_b128 v[194:197], v185 offset:18432
	ds_read_b128 v[198:201], v185 offset:18448
	ds_read_b128 v[202:205], v185 offset:20480
	ds_read_b128 v[206:209], v185 offset:20496
	ds_read_b128 v[216:219], v185 offset:22528
	ds_read_b128 v[220:223], v185 offset:22544
	global_load_lds_dwordx4 v[174:175], off
	v_lshl_add_u64 v[176:177], s[14:15], 0, v[168:169]
	s_mov_b32 m0, s26
	s_addc_u32 s57, s15, 0
	global_load_lds_dwordx4 v[176:177], off
	v_lshl_add_u64 v[178:179], s[56:57], 0, v[2:3]
	s_mov_b32 m0, s27
	v_lshl_add_u64 v[180:181], s[24:25], 0, v[166:167]
	global_load_lds_dwordx4 v[178:179], off
	v_lshl_add_u64 v[178:179], s[56:57], 0, v[168:169]
	s_mov_b32 m0, s34
	s_nop 0
	global_load_lds_dwordx4 v[178:179], off
	v_lshl_add_u64 v[178:179], s[24:25], 0, v[164:165]
	s_mov_b32 m0, s37
	s_nop 0
	global_load_lds_dwordx4 v[178:179], off
	s_mov_b32 m0, s38
	s_nop 0
	global_load_lds_dwordx4 v[180:181], off
	s_waitcnt vmcnt(8)
	s_waitcnt lgkmcnt(0)
	s_barrier
	s_setprio 1
	s_waitcnt lgkmcnt(0)
	v_mfma_scale_f32_16x16x128_f8f6f4 v[96:99], v[28:35], v[186:193], v[96:99], v183, v182 op_sel_hi:[0,0,0]
	v_mfma_scale_f32_16x16x128_f8f6f4 v[92:95], v[20:27], v[186:193], v[92:95], v183, v182 op_sel_hi:[0,0,0]
	v_mfma_scale_f32_16x16x128_f8f6f4 v[80:83], v[28:35], v[194:201], v[80:83], v183, v182 op_sel_hi:[0,0,0]
	v_mfma_scale_f32_16x16x128_f8f6f4 v[76:79], v[20:27], v[194:201], v[76:79], v183, v182 op_sel_hi:[0,0,0]
	v_mfma_scale_f32_16x16x128_f8f6f4 v[64:67], v[28:35], v[202:209], v[64:67], v183, v182 op_sel_hi:[0,0,0]
	v_mfma_scale_f32_16x16x128_f8f6f4 v[60:63], v[20:27], v[202:209], v[60:63], v183, v182 op_sel_hi:[0,0,0]
	v_mfma_scale_f32_16x16x128_f8f6f4 v[48:51], v[28:35], v[216:223], v[48:51], v183, v182 op_sel_hi:[0,0,0]
	v_mfma_scale_f32_16x16x128_f8f6f4 v[44:47], v[20:27], v[216:223], v[44:47], v183, v182 op_sel_hi:[0,0,0]
	s_setprio 0
	s_setprio 1
	v_mfma_scale_f32_16x16x128_f8f6f4 v[88:91], v[12:19], v[186:193], v[88:91], v183, v182 op_sel_hi:[0,0,0]
	v_mfma_scale_f32_16x16x128_f8f6f4 v[84:87], v[4:11], v[186:193], v[84:87], v183, v182 op_sel_hi:[0,0,0]
	v_mfma_scale_f32_16x16x128_f8f6f4 v[72:75], v[12:19], v[194:201], v[72:75], v183, v182 op_sel_hi:[0,0,0]
	v_mfma_scale_f32_16x16x128_f8f6f4 v[68:71], v[4:11], v[194:201], v[68:71], v183, v182 op_sel_hi:[0,0,0]
	v_mfma_scale_f32_16x16x128_f8f6f4 v[56:59], v[12:19], v[202:209], v[56:59], v183, v182 op_sel_hi:[0,0,0]
	v_mfma_scale_f32_16x16x128_f8f6f4 v[52:55], v[4:11], v[202:209], v[52:55], v183, v182 op_sel_hi:[0,0,0]
	v_mfma_scale_f32_16x16x128_f8f6f4 v[40:43], v[12:19], v[216:223], v[40:43], v183, v182 op_sel_hi:[0,0,0]
	v_mfma_scale_f32_16x16x128_f8f6f4 v[36:39], v[4:11], v[216:223], v[36:39], v183, v182 op_sel_hi:[0,0,0]
	s_setprio 0
	s_barrier
	v_add_u32_e32 v4, s20, v184
	v_add_u32_e32 v8, s21, v184
	ds_read_b128 v[28:31], v4
	ds_read_b128 v[32:35], v4 offset:16
	ds_read_b128 v[20:23], v4 offset:2048
	ds_read_b128 v[24:27], v4 offset:2064
	ds_read_b128 v[12:15], v8
	ds_read_b128 v[16:19], v8 offset:16
	ds_read_b128 v[4:7], v8 offset:2048
	ds_read_b128 v[8:11], v8 offset:2064
	s_add_u32 s24, s24, 0x40000
	s_addc_u32 s25, s25, 0
	s_mov_b32 m0, s39
	v_lshl_add_u64 v[210:211], s[24:25], 0, v[164:165]
	ds_read_b128 v[186:189], v185 offset:32768
	ds_read_b128 v[190:193], v185 offset:32784
	ds_read_b128 v[194:197], v185 offset:34816
	ds_read_b128 v[198:201], v185 offset:34832
	ds_read_b128 v[202:205], v185 offset:36864
	ds_read_b128 v[206:209], v185 offset:36880
	ds_read_b128 v[216:219], v185 offset:38912
	ds_read_b128 v[220:223], v185 offset:38928
	global_load_lds_dwordx4 v[210:211], off
	v_lshl_add_u64 v[210:211], s[24:25], 0, v[166:167]
	s_mov_b32 m0, s40
	s_nop 0
	global_load_lds_dwordx4 v[210:211], off
	s_waitcnt vmcnt(8)
	s_waitcnt lgkmcnt(0)
	s_barrier
	s_setprio 1
	s_waitcnt lgkmcnt(0)
	v_mfma_scale_f32_16x16x128_f8f6f4 v[160:163], v[28:35], v[186:193], v[160:163], v183, v182 op_sel_hi:[0,0,0]
	v_mfma_scale_f32_16x16x128_f8f6f4 v[156:159], v[20:27], v[186:193], v[156:159], v183, v182 op_sel_hi:[0,0,0]
	v_mfma_scale_f32_16x16x128_f8f6f4 v[144:147], v[28:35], v[194:201], v[144:147], v183, v182 op_sel_hi:[0,0,0]
	v_mfma_scale_f32_16x16x128_f8f6f4 v[140:143], v[20:27], v[194:201], v[140:143], v183, v182 op_sel_hi:[0,0,0]
	v_mfma_scale_f32_16x16x128_f8f6f4 v[128:131], v[28:35], v[202:209], v[128:131], v183, v182 op_sel_hi:[0,0,0]
	v_mfma_scale_f32_16x16x128_f8f6f4 v[124:127], v[20:27], v[202:209], v[124:127], v183, v182 op_sel_hi:[0,0,0]
	v_mfma_scale_f32_16x16x128_f8f6f4 v[112:115], v[28:35], v[216:223], v[112:115], v183, v182 op_sel_hi:[0,0,0]
	v_mfma_scale_f32_16x16x128_f8f6f4 v[108:111], v[20:27], v[216:223], v[108:111], v183, v182 op_sel_hi:[0,0,0]
	s_setprio 0
	s_setprio 1
	v_mfma_scale_f32_16x16x128_f8f6f4 v[152:155], v[12:19], v[186:193], v[152:155], v183, v182 op_sel_hi:[0,0,0]
	v_mfma_scale_f32_16x16x128_f8f6f4 v[148:151], v[4:11], v[186:193], v[148:151], v183, v182 op_sel_hi:[0,0,0]
	v_mfma_scale_f32_16x16x128_f8f6f4 v[136:139], v[12:19], v[194:201], v[136:139], v183, v182 op_sel_hi:[0,0,0]
	v_mfma_scale_f32_16x16x128_f8f6f4 v[132:135], v[4:11], v[194:201], v[132:135], v183, v182 op_sel_hi:[0,0,0]
	v_mfma_scale_f32_16x16x128_f8f6f4 v[120:123], v[12:19], v[202:209], v[120:123], v183, v182 op_sel_hi:[0,0,0]
	v_mfma_scale_f32_16x16x128_f8f6f4 v[116:119], v[4:11], v[202:209], v[116:119], v183, v182 op_sel_hi:[0,0,0]
	v_mfma_scale_f32_16x16x128_f8f6f4 v[104:107], v[12:19], v[216:223], v[104:107], v183, v182 op_sel_hi:[0,0,0]
	v_mfma_scale_f32_16x16x128_f8f6f4 v[100:103], v[4:11], v[216:223], v[100:103], v183, v182 op_sel_hi:[0,0,0]
	s_setprio 0
	s_barrier
	s_mov_b32 m0, s42
	v_lshl_add_u64 v[174:175], v[174:175], 0, s[64:65]
	s_add_u32 s14, s14, 0x40080
	ds_read_b128 v[186:189], v185 offset:49152
	ds_read_b128 v[190:193], v185 offset:49168
	ds_read_b128 v[194:197], v185 offset:51200
	ds_read_b128 v[198:201], v185 offset:51216
	ds_read_b128 v[202:205], v185 offset:53248
	ds_read_b128 v[206:209], v185 offset:53264
	ds_read_b128 v[216:219], v185 offset:55296
	ds_read_b128 v[220:223], v185 offset:55312
	global_load_lds_dwordx4 v[174:175], off
	v_lshl_add_u64 v[174:175], v[176:177], 0, s[64:65]
	s_mov_b32 m0, s43
	s_addc_u32 s15, s15, 0
	global_load_lds_dwordx4 v[174:175], off
	v_lshl_add_u64 v[174:175], s[14:15], 0, v[2:3]
	s_mov_b32 m0, s46
	s_nop 0
	global_load_lds_dwordx4 v[174:175], off
	v_lshl_add_u64 v[174:175], s[14:15], 0, v[168:169]
	s_mov_b32 m0, s47
	s_nop 0
	global_load_lds_dwordx4 v[174:175], off
	v_lshl_add_u64 v[174:175], v[178:179], 0, s[64:65]
	s_mov_b32 m0, s44
	s_nop 0
	global_load_lds_dwordx4 v[174:175], off
	v_lshl_add_u64 v[174:175], v[180:181], 0, s[64:65]
	s_mov_b32 m0, s45
	s_nop 0
	global_load_lds_dwordx4 v[174:175], off
	s_waitcnt vmcnt(8)
	s_waitcnt lgkmcnt(0)
	s_barrier
	s_setprio 1
	s_waitcnt lgkmcnt(0)
	v_mfma_scale_f32_16x16x128_f8f6f4 v[96:99], v[28:35], v[186:193], v[96:99], v183, v182 op_sel_hi:[0,0,0]
	v_mfma_scale_f32_16x16x128_f8f6f4 v[92:95], v[20:27], v[186:193], v[92:95], v183, v182 op_sel_hi:[0,0,0]
	v_mfma_scale_f32_16x16x128_f8f6f4 v[80:83], v[28:35], v[194:201], v[80:83], v183, v182 op_sel_hi:[0,0,0]
	v_mfma_scale_f32_16x16x128_f8f6f4 v[76:79], v[20:27], v[194:201], v[76:79], v183, v182 op_sel_hi:[0,0,0]
	v_mfma_scale_f32_16x16x128_f8f6f4 v[64:67], v[28:35], v[202:209], v[64:67], v183, v182 op_sel_hi:[0,0,0]
	v_mfma_scale_f32_16x16x128_f8f6f4 v[60:63], v[20:27], v[202:209], v[60:63], v183, v182 op_sel_hi:[0,0,0]
	v_mfma_scale_f32_16x16x128_f8f6f4 v[48:51], v[28:35], v[216:223], v[48:51], v183, v182 op_sel_hi:[0,0,0]
	v_mfma_scale_f32_16x16x128_f8f6f4 v[44:47], v[20:27], v[216:223], v[44:47], v183, v182 op_sel_hi:[0,0,0]
	s_setprio 0
	s_setprio 1
	v_mfma_scale_f32_16x16x128_f8f6f4 v[88:91], v[12:19], v[186:193], v[88:91], v183, v182 op_sel_hi:[0,0,0]
	v_mfma_scale_f32_16x16x128_f8f6f4 v[84:87], v[4:11], v[186:193], v[84:87], v183, v182 op_sel_hi:[0,0,0]
	v_mfma_scale_f32_16x16x128_f8f6f4 v[72:75], v[12:19], v[194:201], v[72:75], v183, v182 op_sel_hi:[0,0,0]
	v_mfma_scale_f32_16x16x128_f8f6f4 v[68:71], v[4:11], v[194:201], v[68:71], v183, v182 op_sel_hi:[0,0,0]
	s_add_i32 s52, s52, 2
	v_mfma_scale_f32_16x16x128_f8f6f4 v[56:59], v[12:19], v[202:209], v[56:59], v183, v182 op_sel_hi:[0,0,0]
	s_add_u32 s12, s12, 0x100
	s_addc_u32 s13, s13, 0
	v_mfma_scale_f32_16x16x128_f8f6f4 v[52:55], v[4:11], v[202:209], v[52:55], v183, v182 op_sel_hi:[0,0,0]
	s_cmp_gt_u32 s52, 13
	v_mfma_scale_f32_16x16x128_f8f6f4 v[40:43], v[12:19], v[216:223], v[40:43], v183, v182 op_sel_hi:[0,0,0]
	v_mfma_scale_f32_16x16x128_f8f6f4 v[36:39], v[4:11], v[216:223], v[36:39], v183, v182 op_sel_hi:[0,0,0]
	s_setprio 0
	s_barrier
	s_cbranch_scc0 .LBB0_2890
	s_cmpk_lt_u32 s22, 0x100
	s_cbranch_scc0 .LBB0_2893
	s_barrier

.LBB0_2896:
	v_add_u32_e32 v148, s18, v126
	v_add_u32_e32 v172, s19, v126
	s_add_u32 s12, s46, s8
	ds_read_b128 v[128:131], v148
	ds_read_b128 v[132:135], v148 offset:1024
	ds_read_b128 v[140:143], v148 offset:2048
	ds_read_b128 v[148:151], v148 offset:3072
	ds_read_b128 v[160:163], v172
	ds_read_b128 v[164:167], v172 offset:1024
	ds_read_b128 v[168:171], v172 offset:2048
	ds_read_b128 v[172:175], v172 offset:3072
	s_addc_u32 s13, s47, s9
	s_add_u32 s12, s12, 0x34400100
	s_addc_u32 s13, s13, 0
	s_add_u32 s16, s48, s8
	s_addc_u32 s51, s49, s9
	s_cmpk_eq_i32 s8, 0xf00
	s_cselect_b32 s15, s11, s13
	s_cselect_b32 s14, s10, s12
	s_cselect_b32 s13, s3, s51
	s_cselect_b32 s12, s2, s16
	v_lshl_add_u64 v[208:209], v[122:123], 0, s[8:9]
	s_add_i32 m0, s27, 0xc000
	ds_read_b128 v[176:179], v127
	ds_read_b128 v[180:183], v127 offset:1024
	ds_read_b128 v[184:187], v127 offset:2048
	ds_read_b128 v[188:191], v127 offset:3072
	ds_read_b128 v[192:195], v127 offset:4096
	ds_read_b128 v[196:199], v127 offset:5120
	ds_read_b128 v[200:203], v127 offset:6144
	ds_read_b128 v[204:207], v127 offset:7168
	global_load_lds_dwordx4 v[208:209], off
	v_lshl_add_u64 v[208:209], v[124:125], 0, s[8:9]
	s_add_i32 m0, s27, 0xe000
	s_nop 0
	global_load_lds_dwordx4 v[208:209], off
	s_waitcnt vmcnt(8)
	s_waitcnt lgkmcnt(0)
	s_barrier
	s_setprio 1
	s_waitcnt lgkmcnt(0)
	v_mfma_f32_16x16x32_bf16 v[156:159], v[128:131], v[176:179], v[156:159]
	v_mfma_f32_16x16x32_bf16 v[156:159], v[132:135], v[180:183], v[156:159]
	v_mfma_f32_16x16x32_bf16 v[112:115], v[128:131], v[184:187], v[112:115]
	v_mfma_f32_16x16x32_bf16 v[112:115], v[132:135], v[188:191], v[112:115]
	v_mfma_f32_16x16x32_bf16 v[96:99], v[128:131], v[192:195], v[96:99]
	v_mfma_f32_16x16x32_bf16 v[96:99], v[132:135], v[196:199], v[96:99]
	v_mfma_f32_16x16x32_bf16 v[80:83], v[128:131], v[200:203], v[80:83]
	v_mfma_f32_16x16x32_bf16 v[80:83], v[132:135], v[204:207], v[80:83]
	v_mfma_f32_16x16x32_bf16 v[76:79], v[140:143], v[200:203], v[76:79]
	v_mfma_f32_16x16x32_bf16 v[76:79], v[148:151], v[204:207], v[76:79]
	v_mfma_f32_16x16x32_bf16 v[92:95], v[140:143], v[192:195], v[92:95]
	v_mfma_f32_16x16x32_bf16 v[92:95], v[148:151], v[196:199], v[92:95]
	v_mfma_f32_16x16x32_bf16 v[108:111], v[140:143], v[184:187], v[108:111]
	v_mfma_f32_16x16x32_bf16 v[108:111], v[148:151], v[188:191], v[108:111]
	v_mfma_f32_16x16x32_bf16 v[152:155], v[140:143], v[176:179], v[152:155]
	v_mfma_f32_16x16x32_bf16 v[152:155], v[148:151], v[180:183], v[152:155]
	s_setprio 0
	s_setprio 1
	v_mfma_f32_16x16x32_bf16 v[144:147], v[160:163], v[176:179], v[144:147]
	v_mfma_f32_16x16x32_bf16 v[144:147], v[164:167], v[180:183], v[144:147]
	v_mfma_f32_16x16x32_bf16 v[104:107], v[160:163], v[184:187], v[104:107]
	v_mfma_f32_16x16x32_bf16 v[104:107], v[164:167], v[188:191], v[104:107]
	v_mfma_f32_16x16x32_bf16 v[88:91], v[160:163], v[192:195], v[88:91]
	v_mfma_f32_16x16x32_bf16 v[88:91], v[164:167], v[196:199], v[88:91]
	v_mfma_f32_16x16x32_bf16 v[72:75], v[160:163], v[200:203], v[72:75]
	v_mfma_f32_16x16x32_bf16 v[72:75], v[164:167], v[204:207], v[72:75]
	v_mfma_f32_16x16x32_bf16 v[68:71], v[168:171], v[200:203], v[68:71]
	v_mfma_f32_16x16x32_bf16 v[68:71], v[172:175], v[204:207], v[68:71]
	v_mfma_f32_16x16x32_bf16 v[84:87], v[168:171], v[192:195], v[84:87]
	v_mfma_f32_16x16x32_bf16 v[84:87], v[172:175], v[196:199], v[84:87]
	v_mfma_f32_16x16x32_bf16 v[100:103], v[168:171], v[184:187], v[100:103]
	v_mfma_f32_16x16x32_bf16 v[100:103], v[172:175], v[188:191], v[100:103]
	v_mfma_f32_16x16x32_bf16 v[136:139], v[168:171], v[176:179], v[136:139]
	v_mfma_f32_16x16x32_bf16 v[136:139], v[172:175], v[180:183], v[136:139]
	s_setprio 0
	s_barrier
	s_mov_b32 m0, s23
	v_lshl_add_u64 v[208:209], s[12:13], 0, v[2:3]
	s_add_u32 s52, s12, 0x80000
	ds_read_b128 v[176:179], v127 offset:16384
	ds_read_b128 v[180:183], v127 offset:17408
	ds_read_b128 v[184:187], v127 offset:18432
	ds_read_b128 v[188:191], v127 offset:19456
	ds_read_b128 v[192:195], v127 offset:20480
	ds_read_b128 v[196:199], v127 offset:21504
	ds_read_b128 v[200:203], v127 offset:22528
	ds_read_b128 v[204:207], v127 offset:23552
	global_load_lds_dwordx4 v[208:209], off
	v_lshl_add_u64 v[210:211], s[12:13], 0, v[120:121]
	s_mov_b32 m0, s24
	s_addc_u32 s53, s13, 0
	global_load_lds_dwordx4 v[210:211], off
	v_lshl_add_u64 v[216:217], s[52:53], 0, v[2:3]
	s_mov_b32 m0, s25
	v_lshl_add_u64 v[218:219], s[14:15], 0, v[118:119]
	global_load_lds_dwordx4 v[216:217], off
	v_lshl_add_u64 v[216:217], s[52:53], 0, v[120:121]
	s_mov_b32 m0, s26
	s_nop 0
	global_load_lds_dwordx4 v[216:217], off
	v_lshl_add_u64 v[216:217], s[14:15], 0, v[116:117]
	s_mov_b32 m0, s27
	s_nop 0
	global_load_lds_dwordx4 v[216:217], off
	s_mov_b32 m0, s35
	s_nop 0
	global_load_lds_dwordx4 v[218:219], off
	s_waitcnt vmcnt(8)
	s_waitcnt lgkmcnt(0)
	s_barrier
	s_setprio 1
	s_waitcnt lgkmcnt(0)
	v_mfma_f32_16x16x32_bf16 v[64:67], v[128:131], v[176:179], v[64:67]
	v_mfma_f32_16x16x32_bf16 v[64:67], v[132:135], v[180:183], v[64:67]
	v_mfma_f32_16x16x32_bf16 v[48:51], v[128:131], v[184:187], v[48:51]
	v_mfma_f32_16x16x32_bf16 v[48:51], v[132:135], v[188:191], v[48:51]
	v_mfma_f32_16x16x32_bf16 v[32:35], v[128:131], v[192:195], v[32:35]
	v_mfma_f32_16x16x32_bf16 v[32:35], v[132:135], v[196:199], v[32:35]
	v_mfma_f32_16x16x32_bf16 v[16:19], v[128:131], v[200:203], v[16:19]
	v_mfma_f32_16x16x32_bf16 v[16:19], v[132:135], v[204:207], v[16:19]
	v_mfma_f32_16x16x32_bf16 v[12:15], v[140:143], v[200:203], v[12:15]
	v_mfma_f32_16x16x32_bf16 v[12:15], v[148:151], v[204:207], v[12:15]
	v_mfma_f32_16x16x32_bf16 v[28:31], v[140:143], v[192:195], v[28:31]
	v_mfma_f32_16x16x32_bf16 v[28:31], v[148:151], v[196:199], v[28:31]
	v_mfma_f32_16x16x32_bf16 v[44:47], v[140:143], v[184:187], v[44:47]
	v_mfma_f32_16x16x32_bf16 v[44:47], v[148:151], v[188:191], v[44:47]
	v_mfma_f32_16x16x32_bf16 v[60:63], v[140:143], v[176:179], v[60:63]
	v_mfma_f32_16x16x32_bf16 v[60:63], v[148:151], v[180:183], v[60:63]
	s_setprio 0
	s_setprio 1
	v_mfma_f32_16x16x32_bf16 v[56:59], v[160:163], v[176:179], v[56:59]
	v_mfma_f32_16x16x32_bf16 v[56:59], v[164:167], v[180:183], v[56:59]
	v_mfma_f32_16x16x32_bf16 v[40:43], v[160:163], v[184:187], v[40:43]
	v_mfma_f32_16x16x32_bf16 v[40:43], v[164:167], v[188:191], v[40:43]
	v_mfma_f32_16x16x32_bf16 v[24:27], v[160:163], v[192:195], v[24:27]
	v_mfma_f32_16x16x32_bf16 v[24:27], v[164:167], v[196:199], v[24:27]
	v_mfma_f32_16x16x32_bf16 v[8:11], v[160:163], v[200:203], v[8:11]
	v_mfma_f32_16x16x32_bf16 v[8:11], v[164:167], v[204:207], v[8:11]
	v_mfma_f32_16x16x32_bf16 v[4:7], v[168:171], v[200:203], v[4:7]
	v_mfma_f32_16x16x32_bf16 v[4:7], v[172:175], v[204:207], v[4:7]
	v_mfma_f32_16x16x32_bf16 v[20:23], v[168:171], v[192:195], v[20:23]
	v_mfma_f32_16x16x32_bf16 v[20:23], v[172:175], v[196:199], v[20:23]
	v_mfma_f32_16x16x32_bf16 v[36:39], v[168:171], v[184:187], v[36:39]
	v_mfma_f32_16x16x32_bf16 v[36:39], v[172:175], v[188:191], v[36:39]
	v_mfma_f32_16x16x32_bf16 v[52:55], v[168:171], v[176:179], v[52:55]
	v_mfma_f32_16x16x32_bf16 v[52:55], v[172:175], v[180:183], v[52:55]
	s_setprio 0
	s_barrier
	v_add_u32_e32 v148, s20, v126
	v_add_u32_e32 v172, s21, v126
	ds_read_b128 v[128:131], v148
	ds_read_b128 v[132:135], v148 offset:1024
	ds_read_b128 v[140:143], v148 offset:2048
	ds_read_b128 v[148:151], v148 offset:3072
	ds_read_b128 v[160:163], v172
	ds_read_b128 v[164:167], v172 offset:1024
	ds_read_b128 v[168:171], v172 offset:2048
	ds_read_b128 v[172:175], v172 offset:3072
	s_add_u32 s14, s14, 0x80000
	s_addc_u32 s15, s15, 0
	s_mov_b32 m0, s37
	v_lshl_add_u64 v[220:221], s[14:15], 0, v[116:117]
	ds_read_b128 v[176:179], v127 offset:32768
	ds_read_b128 v[180:183], v127 offset:33792
	ds_read_b128 v[184:187], v127 offset:34816
	ds_read_b128 v[188:191], v127 offset:35840
	ds_read_b128 v[192:195], v127 offset:36864
	ds_read_b128 v[196:199], v127 offset:37888
	ds_read_b128 v[200:203], v127 offset:38912
	ds_read_b128 v[204:207], v127 offset:39936
	global_load_lds_dwordx4 v[220:221], off
	v_lshl_add_u64 v[220:221], s[14:15], 0, v[118:119]
	s_mov_b32 m0, s38
	s_nop 0
	global_load_lds_dwordx4 v[220:221], off
	s_waitcnt vmcnt(8)
	s_waitcnt lgkmcnt(0)
	s_barrier
	s_setprio 1
	s_waitcnt lgkmcnt(0)
	v_mfma_f32_16x16x32_bf16 v[156:159], v[128:131], v[176:179], v[156:159]
	v_mfma_f32_16x16x32_bf16 v[156:159], v[132:135], v[180:183], v[156:159]
	v_mfma_f32_16x16x32_bf16 v[112:115], v[128:131], v[184:187], v[112:115]
	v_mfma_f32_16x16x32_bf16 v[112:115], v[132:135], v[188:191], v[112:115]
	v_mfma_f32_16x16x32_bf16 v[96:99], v[128:131], v[192:195], v[96:99]
	v_mfma_f32_16x16x32_bf16 v[96:99], v[132:135], v[196:199], v[96:99]
	v_mfma_f32_16x16x32_bf16 v[80:83], v[128:131], v[200:203], v[80:83]
	v_mfma_f32_16x16x32_bf16 v[80:83], v[132:135], v[204:207], v[80:83]
	v_mfma_f32_16x16x32_bf16 v[76:79], v[140:143], v[200:203], v[76:79]
	v_mfma_f32_16x16x32_bf16 v[76:79], v[148:151], v[204:207], v[76:79]
	v_mfma_f32_16x16x32_bf16 v[92:95], v[140:143], v[192:195], v[92:95]
	v_mfma_f32_16x16x32_bf16 v[92:95], v[148:151], v[196:199], v[92:95]
	v_mfma_f32_16x16x32_bf16 v[108:111], v[140:143], v[184:187], v[108:111]
	v_mfma_f32_16x16x32_bf16 v[108:111], v[148:151], v[188:191], v[108:111]
	v_mfma_f32_16x16x32_bf16 v[152:155], v[140:143], v[176:179], v[152:155]
	v_mfma_f32_16x16x32_bf16 v[152:155], v[148:151], v[180:183], v[152:155]
	s_setprio 0
	s_setprio 1
	v_mfma_f32_16x16x32_bf16 v[144:147], v[160:163], v[176:179], v[144:147]
	v_mfma_f32_16x16x32_bf16 v[144:147], v[164:167], v[180:183], v[144:147]
	v_mfma_f32_16x16x32_bf16 v[104:107], v[160:163], v[184:187], v[104:107]
	v_mfma_f32_16x16x32_bf16 v[104:107], v[164:167], v[188:191], v[104:107]
	v_mfma_f32_16x16x32_bf16 v[88:91], v[160:163], v[192:195], v[88:91]
	v_mfma_f32_16x16x32_bf16 v[88:91], v[164:167], v[196:199], v[88:91]
	v_mfma_f32_16x16x32_bf16 v[72:75], v[160:163], v[200:203], v[72:75]
	v_mfma_f32_16x16x32_bf16 v[72:75], v[164:167], v[204:207], v[72:75]
	v_mfma_f32_16x16x32_bf16 v[68:71], v[168:171], v[200:203], v[68:71]
	v_mfma_f32_16x16x32_bf16 v[68:71], v[172:175], v[204:207], v[68:71]
	v_mfma_f32_16x16x32_bf16 v[84:87], v[168:171], v[192:195], v[84:87]
	v_mfma_f32_16x16x32_bf16 v[84:87], v[172:175], v[196:199], v[84:87]
	v_mfma_f32_16x16x32_bf16 v[100:103], v[168:171], v[184:187], v[100:103]
	v_mfma_f32_16x16x32_bf16 v[100:103], v[172:175], v[188:191], v[100:103]
	v_mfma_f32_16x16x32_bf16 v[136:139], v[168:171], v[176:179], v[136:139]
	v_mfma_f32_16x16x32_bf16 v[136:139], v[172:175], v[180:183], v[136:139]
	s_setprio 0
	s_barrier
	s_mov_b32 m0, s40
	v_lshl_add_u64 v[208:209], v[208:209], 0, s[64:65]
	s_add_u32 s12, s12, 0x80080
	ds_read_b128 v[176:179], v127 offset:49152
	ds_read_b128 v[180:183], v127 offset:50176
	ds_read_b128 v[184:187], v127 offset:51200
	ds_read_b128 v[188:191], v127 offset:52224
	ds_read_b128 v[192:195], v127 offset:53248
	ds_read_b128 v[196:199], v127 offset:54272
	ds_read_b128 v[200:203], v127 offset:55296
	ds_read_b128 v[204:207], v127 offset:56320
	global_load_lds_dwordx4 v[208:209], off
	v_lshl_add_u64 v[208:209], v[210:211], 0, s[64:65]
	s_mov_b32 m0, s41
	s_addc_u32 s13, s13, 0
	global_load_lds_dwordx4 v[208:209], off
	v_lshl_add_u64 v[208:209], s[12:13], 0, v[2:3]
	s_mov_b32 m0, s44
	s_nop 0
	global_load_lds_dwordx4 v[208:209], off
	v_lshl_add_u64 v[208:209], s[12:13], 0, v[120:121]
	s_mov_b32 m0, s45
	s_nop 0
	global_load_lds_dwordx4 v[208:209], off
	v_lshl_add_u64 v[208:209], v[216:217], 0, s[64:65]
	s_mov_b32 m0, s42
	s_nop 0
	global_load_lds_dwordx4 v[208:209], off
	v_lshl_add_u64 v[208:209], v[218:219], 0, s[64:65]
	s_mov_b32 m0, s43
	s_nop 0
	global_load_lds_dwordx4 v[208:209], off
	s_waitcnt vmcnt(8)
	s_waitcnt lgkmcnt(0)
	s_barrier
	s_setprio 1
	s_waitcnt lgkmcnt(0)
	v_mfma_f32_16x16x32_bf16 v[64:67], v[128:131], v[176:179], v[64:67]
	v_mfma_f32_16x16x32_bf16 v[64:67], v[132:135], v[180:183], v[64:67]
	v_mfma_f32_16x16x32_bf16 v[48:51], v[128:131], v[184:187], v[48:51]
	v_mfma_f32_16x16x32_bf16 v[48:51], v[132:135], v[188:191], v[48:51]
	v_mfma_f32_16x16x32_bf16 v[32:35], v[128:131], v[192:195], v[32:35]
	v_mfma_f32_16x16x32_bf16 v[32:35], v[132:135], v[196:199], v[32:35]
	v_mfma_f32_16x16x32_bf16 v[16:19], v[128:131], v[200:203], v[16:19]
	v_mfma_f32_16x16x32_bf16 v[16:19], v[132:135], v[204:207], v[16:19]
	v_mfma_f32_16x16x32_bf16 v[12:15], v[140:143], v[200:203], v[12:15]
	v_mfma_f32_16x16x32_bf16 v[12:15], v[148:151], v[204:207], v[12:15]
	v_mfma_f32_16x16x32_bf16 v[28:31], v[140:143], v[192:195], v[28:31]
	v_mfma_f32_16x16x32_bf16 v[28:31], v[148:151], v[196:199], v[28:31]
	v_mfma_f32_16x16x32_bf16 v[44:47], v[140:143], v[184:187], v[44:47]
	v_mfma_f32_16x16x32_bf16 v[44:47], v[148:151], v[188:191], v[44:47]
	v_mfma_f32_16x16x32_bf16 v[60:63], v[140:143], v[176:179], v[60:63]
	v_mfma_f32_16x16x32_bf16 v[60:63], v[148:151], v[180:183], v[60:63]
	s_setprio 0
	s_setprio 1
	v_mfma_f32_16x16x32_bf16 v[56:59], v[160:163], v[176:179], v[56:59]
	v_mfma_f32_16x16x32_bf16 v[56:59], v[164:167], v[180:183], v[56:59]
	v_mfma_f32_16x16x32_bf16 v[40:43], v[160:163], v[184:187], v[40:43]
	v_mfma_f32_16x16x32_bf16 v[40:43], v[164:167], v[188:191], v[40:43]
	v_mfma_f32_16x16x32_bf16 v[24:27], v[160:163], v[192:195], v[24:27]
	v_mfma_f32_16x16x32_bf16 v[24:27], v[164:167], v[196:199], v[24:27]
	v_mfma_f32_16x16x32_bf16 v[8:11], v[160:163], v[200:203], v[8:11]
	v_mfma_f32_16x16x32_bf16 v[8:11], v[164:167], v[204:207], v[8:11]
	s_add_i32 s50, s50, 2
	v_mfma_f32_16x16x32_bf16 v[4:7], v[168:171], v[200:203], v[4:7]
	v_mfma_f32_16x16x32_bf16 v[4:7], v[172:175], v[204:207], v[4:7]
	s_add_u32 s8, s8, 0x100
	s_addc_u32 s9, s9, 0
	v_mfma_f32_16x16x32_bf16 v[20:23], v[168:171], v[192:195], v[20:23]
	v_mfma_f32_16x16x32_bf16 v[20:23], v[172:175], v[196:199], v[20:23]
	s_cmp_gt_u32 s50, 29
	v_mfma_f32_16x16x32_bf16 v[36:39], v[168:171], v[184:187], v[36:39]
	v_mfma_f32_16x16x32_bf16 v[36:39], v[172:175], v[188:191], v[36:39]
	v_mfma_f32_16x16x32_bf16 v[52:55], v[168:171], v[176:179], v[52:55]
	v_mfma_f32_16x16x32_bf16 v[52:55], v[172:175], v[180:183], v[52:55]
	s_setprio 0
	s_barrier
	s_cbranch_scc0 .LBB0_2896
	s_cmpk_lt_u32 s22, 0x100
	s_cbranch_scc0 .LBB0_2899
	s_barrier

.LBB0_3116:
	v_add_u32_e32 v142, s26, v144
	ds_read_b128 v[146:149], v142
	ds_read_b128 v[150:153], v142 offset:1024
	ds_read_b128 v[154:157], v142 offset:2048
	ds_read_b128 v[158:161], v142 offset:3072
	v_add_u32_e32 v142, s40, v144
	ds_read_b128 v[162:165], v142
	ds_read_b128 v[166:169], v142 offset:1024
	ds_read_b128 v[170:173], v142 offset:2048
	ds_read_b128 v[174:177], v142 offset:3072
	s_add_u32 s18, s34, 0xfff80080
	s_addc_u32 s19, s35, -1
	s_cmp_eq_u32 s74, 28
	s_cselect_b32 s39, s13, s19
	s_cselect_b32 s38, s69, s18
	s_cselect_b32 s19, s11, s73
	s_cselect_b32 s18, s70, s71
	v_lshl_add_u64 v[142:143], s[34:35], 0, v[138:139]
	s_add_i32 m0, s43, 0xc000
	ds_read_b128 v[178:181], v145
	ds_read_b128 v[182:185], v145 offset:1024
	ds_read_b128 v[186:189], v145 offset:2048
	ds_read_b128 v[190:193], v145 offset:3072
	ds_read_b128 v[194:197], v145 offset:4096
	ds_read_b128 v[198:201], v145 offset:5120
	ds_read_b128 v[202:205], v145 offset:6144
	ds_read_b128 v[206:209], v145 offset:7168
	global_load_lds_dwordx4 v[142:143], off
	v_lshl_add_u64 v[142:143], s[34:35], 0, v[140:141]
	s_add_i32 m0, s43, 0xe000
	s_nop 0
	global_load_lds_dwordx4 v[142:143], off
	s_waitcnt vmcnt(8)
	s_waitcnt lgkmcnt(0)
	s_barrier
	s_setprio 1
	s_waitcnt lgkmcnt(0)
	v_mfma_f32_16x16x32_bf16 v[128:131], v[146:149], v[178:181], v[128:131]
	v_mfma_f32_16x16x32_bf16 v[128:131], v[150:153], v[182:185], v[128:131]
	v_mfma_f32_16x16x32_bf16 v[112:115], v[146:149], v[186:189], v[112:115]
	v_mfma_f32_16x16x32_bf16 v[112:115], v[150:153], v[190:193], v[112:115]
	v_mfma_f32_16x16x32_bf16 v[96:99], v[146:149], v[194:197], v[96:99]
	v_mfma_f32_16x16x32_bf16 v[96:99], v[150:153], v[198:201], v[96:99]
	v_mfma_f32_16x16x32_bf16 v[80:83], v[146:149], v[202:205], v[80:83]
	v_mfma_f32_16x16x32_bf16 v[80:83], v[150:153], v[206:209], v[80:83]
	v_mfma_f32_16x16x32_bf16 v[72:75], v[154:157], v[202:205], v[72:75]
	v_mfma_f32_16x16x32_bf16 v[72:75], v[158:161], v[206:209], v[72:75]
	v_mfma_f32_16x16x32_bf16 v[88:91], v[154:157], v[194:197], v[88:91]
	v_mfma_f32_16x16x32_bf16 v[88:91], v[158:161], v[198:201], v[88:91]
	v_mfma_f32_16x16x32_bf16 v[104:107], v[154:157], v[186:189], v[104:107]
	v_mfma_f32_16x16x32_bf16 v[104:107], v[158:161], v[190:193], v[104:107]
	v_mfma_f32_16x16x32_bf16 v[120:123], v[154:157], v[178:181], v[120:123]
	v_mfma_f32_16x16x32_bf16 v[120:123], v[158:161], v[182:185], v[120:123]
	s_setprio 0
	s_setprio 1
	v_mfma_f32_16x16x32_bf16 v[124:127], v[162:165], v[178:181], v[124:127]
	v_mfma_f32_16x16x32_bf16 v[124:127], v[166:169], v[182:185], v[124:127]
	v_mfma_f32_16x16x32_bf16 v[108:111], v[162:165], v[186:189], v[108:111]
	v_mfma_f32_16x16x32_bf16 v[108:111], v[166:169], v[190:193], v[108:111]
	v_mfma_f32_16x16x32_bf16 v[92:95], v[162:165], v[194:197], v[92:95]
	v_mfma_f32_16x16x32_bf16 v[92:95], v[166:169], v[198:201], v[92:95]
	v_mfma_f32_16x16x32_bf16 v[76:79], v[162:165], v[202:205], v[76:79]
	v_mfma_f32_16x16x32_bf16 v[76:79], v[166:169], v[206:209], v[76:79]
	v_mfma_f32_16x16x32_bf16 v[68:71], v[170:173], v[202:205], v[68:71]
	v_mfma_f32_16x16x32_bf16 v[68:71], v[174:177], v[206:209], v[68:71]
	v_mfma_f32_16x16x32_bf16 v[84:87], v[170:173], v[194:197], v[84:87]
	v_mfma_f32_16x16x32_bf16 v[84:87], v[174:177], v[198:201], v[84:87]
	v_mfma_f32_16x16x32_bf16 v[100:103], v[170:173], v[186:189], v[100:103]
	v_mfma_f32_16x16x32_bf16 v[100:103], v[174:177], v[190:193], v[100:103]
	v_mfma_f32_16x16x32_bf16 v[116:119], v[170:173], v[178:181], v[116:119]
	v_mfma_f32_16x16x32_bf16 v[116:119], v[174:177], v[182:185], v[116:119]
	s_setprio 0
	s_barrier
	s_mov_b32 m0, s27
	v_lshl_add_u64 v[142:143], s[18:19], 0, v[2:3]
	s_add_u32 s76, s18, 0x80000
	ds_read_b128 v[178:181], v145 offset:16384
	ds_read_b128 v[182:185], v145 offset:17408
	ds_read_b128 v[186:189], v145 offset:18432
	ds_read_b128 v[190:193], v145 offset:19456
	ds_read_b128 v[194:197], v145 offset:20480
	ds_read_b128 v[198:201], v145 offset:21504
	ds_read_b128 v[202:205], v145 offset:22528
	ds_read_b128 v[206:209], v145 offset:23552
	global_load_lds_dwordx4 v[142:143], off
	v_lshl_add_u64 v[210:211], s[18:19], 0, v[132:133]
	s_mov_b32 m0, s37
	s_addc_u32 s77, s19, 0
	global_load_lds_dwordx4 v[210:211], off
	v_lshl_add_u64 v[212:213], s[76:77], 0, v[2:3]
	s_mov_b32 m0, s41
	v_lshl_add_u64 v[214:215], s[38:39], 0, v[134:135]
	global_load_lds_dwordx4 v[212:213], off
	v_lshl_add_u64 v[212:213], s[76:77], 0, v[132:133]
	s_mov_b32 m0, s42
	s_nop 0
	global_load_lds_dwordx4 v[212:213], off
	v_lshl_add_u64 v[212:213], s[38:39], 0, v[136:137]
	s_mov_b32 m0, s43
	s_nop 0
	global_load_lds_dwordx4 v[212:213], off
	s_mov_b32 m0, s44
	s_nop 0
	global_load_lds_dwordx4 v[214:215], off
	s_waitcnt vmcnt(8)
	s_waitcnt lgkmcnt(0)
	s_barrier
	s_setprio 1
	s_waitcnt lgkmcnt(0)
	v_mfma_f32_16x16x32_bf16 v[64:67], v[146:149], v[178:181], v[64:67]
	v_mfma_f32_16x16x32_bf16 v[64:67], v[150:153], v[182:185], v[64:67]
	v_mfma_f32_16x16x32_bf16 v[48:51], v[146:149], v[186:189], v[48:51]
	v_mfma_f32_16x16x32_bf16 v[48:51], v[150:153], v[190:193], v[48:51]
	v_mfma_f32_16x16x32_bf16 v[32:35], v[146:149], v[194:197], v[32:35]
	v_mfma_f32_16x16x32_bf16 v[32:35], v[150:153], v[198:201], v[32:35]
	v_mfma_f32_16x16x32_bf16 v[16:19], v[146:149], v[202:205], v[16:19]
	v_mfma_f32_16x16x32_bf16 v[16:19], v[150:153], v[206:209], v[16:19]
	v_mfma_f32_16x16x32_bf16 v[8:11], v[154:157], v[202:205], v[8:11]
	v_mfma_f32_16x16x32_bf16 v[8:11], v[158:161], v[206:209], v[8:11]
	v_mfma_f32_16x16x32_bf16 v[24:27], v[154:157], v[194:197], v[24:27]
	v_mfma_f32_16x16x32_bf16 v[24:27], v[158:161], v[198:201], v[24:27]
	v_mfma_f32_16x16x32_bf16 v[40:43], v[154:157], v[186:189], v[40:43]
	v_mfma_f32_16x16x32_bf16 v[40:43], v[158:161], v[190:193], v[40:43]
	v_mfma_f32_16x16x32_bf16 v[56:59], v[154:157], v[178:181], v[56:59]
	v_mfma_f32_16x16x32_bf16 v[56:59], v[158:161], v[182:185], v[56:59]
	s_setprio 0
	s_setprio 1
	v_mfma_f32_16x16x32_bf16 v[60:63], v[162:165], v[178:181], v[60:63]
	v_mfma_f32_16x16x32_bf16 v[60:63], v[166:169], v[182:185], v[60:63]
	v_mfma_f32_16x16x32_bf16 v[44:47], v[162:165], v[186:189], v[44:47]
	v_mfma_f32_16x16x32_bf16 v[44:47], v[166:169], v[190:193], v[44:47]
	v_mfma_f32_16x16x32_bf16 v[28:31], v[162:165], v[194:197], v[28:31]
	v_mfma_f32_16x16x32_bf16 v[28:31], v[166:169], v[198:201], v[28:31]
	v_mfma_f32_16x16x32_bf16 v[12:15], v[162:165], v[202:205], v[12:15]
	v_mfma_f32_16x16x32_bf16 v[12:15], v[166:169], v[206:209], v[12:15]
	v_mfma_f32_16x16x32_bf16 v[4:7], v[170:173], v[202:205], v[4:7]
	v_mfma_f32_16x16x32_bf16 v[4:7], v[174:177], v[206:209], v[4:7]
	v_mfma_f32_16x16x32_bf16 v[20:23], v[170:173], v[194:197], v[20:23]
	v_mfma_f32_16x16x32_bf16 v[20:23], v[174:177], v[198:201], v[20:23]
	v_mfma_f32_16x16x32_bf16 v[36:39], v[170:173], v[186:189], v[36:39]
	v_mfma_f32_16x16x32_bf16 v[36:39], v[174:177], v[190:193], v[36:39]
	v_mfma_f32_16x16x32_bf16 v[52:55], v[170:173], v[178:181], v[52:55]
	v_mfma_f32_16x16x32_bf16 v[52:55], v[174:177], v[182:185], v[52:55]
	s_setprio 0
	s_barrier
	v_add_u32_e32 v158, s49, v144
	v_add_u32_e32 v174, s56, v144
	ds_read_b128 v[146:149], v158
	ds_read_b128 v[150:153], v158 offset:1024
	ds_read_b128 v[154:157], v158 offset:2048
	ds_read_b128 v[158:161], v158 offset:3072
	ds_read_b128 v[162:165], v174
	ds_read_b128 v[166:169], v174 offset:1024
	ds_read_b128 v[170:173], v174 offset:2048
	ds_read_b128 v[174:177], v174 offset:3072
	s_add_u32 s38, s38, 0x80000
	s_addc_u32 s39, s39, 0
	s_mov_b32 m0, s45
	v_lshl_add_u64 v[216:217], s[38:39], 0, v[136:137]
	ds_read_b128 v[178:181], v145 offset:32768
	ds_read_b128 v[182:185], v145 offset:33792
	ds_read_b128 v[186:189], v145 offset:34816
	ds_read_b128 v[190:193], v145 offset:35840
	ds_read_b128 v[194:197], v145 offset:36864
	ds_read_b128 v[198:201], v145 offset:37888
	ds_read_b128 v[202:205], v145 offset:38912
	ds_read_b128 v[206:209], v145 offset:39936
	global_load_lds_dwordx4 v[216:217], off
	v_lshl_add_u64 v[216:217], s[38:39], 0, v[134:135]
	s_mov_b32 m0, s46
	s_nop 0
	global_load_lds_dwordx4 v[216:217], off
	s_waitcnt vmcnt(8)
	s_waitcnt lgkmcnt(0)
	s_barrier
	s_setprio 1
	s_waitcnt lgkmcnt(0)
	v_mfma_f32_16x16x32_bf16 v[128:131], v[146:149], v[178:181], v[128:131]
	v_mfma_f32_16x16x32_bf16 v[128:131], v[150:153], v[182:185], v[128:131]
	v_mfma_f32_16x16x32_bf16 v[112:115], v[146:149], v[186:189], v[112:115]
	v_mfma_f32_16x16x32_bf16 v[112:115], v[150:153], v[190:193], v[112:115]
	v_mfma_f32_16x16x32_bf16 v[96:99], v[146:149], v[194:197], v[96:99]
	v_mfma_f32_16x16x32_bf16 v[96:99], v[150:153], v[198:201], v[96:99]
	v_mfma_f32_16x16x32_bf16 v[80:83], v[146:149], v[202:205], v[80:83]
	v_mfma_f32_16x16x32_bf16 v[80:83], v[150:153], v[206:209], v[80:83]
	v_mfma_f32_16x16x32_bf16 v[72:75], v[154:157], v[202:205], v[72:75]
	v_mfma_f32_16x16x32_bf16 v[72:75], v[158:161], v[206:209], v[72:75]
	v_mfma_f32_16x16x32_bf16 v[88:91], v[154:157], v[194:197], v[88:91]
	v_mfma_f32_16x16x32_bf16 v[88:91], v[158:161], v[198:201], v[88:91]
	v_mfma_f32_16x16x32_bf16 v[104:107], v[154:157], v[186:189], v[104:107]
	v_mfma_f32_16x16x32_bf16 v[104:107], v[158:161], v[190:193], v[104:107]
	v_mfma_f32_16x16x32_bf16 v[120:123], v[154:157], v[178:181], v[120:123]
	v_mfma_f32_16x16x32_bf16 v[120:123], v[158:161], v[182:185], v[120:123]
	s_setprio 0
	s_setprio 1
	v_mfma_f32_16x16x32_bf16 v[124:127], v[162:165], v[178:181], v[124:127]
	v_mfma_f32_16x16x32_bf16 v[124:127], v[166:169], v[182:185], v[124:127]
	v_mfma_f32_16x16x32_bf16 v[108:111], v[162:165], v[186:189], v[108:111]
	v_mfma_f32_16x16x32_bf16 v[108:111], v[166:169], v[190:193], v[108:111]
	v_mfma_f32_16x16x32_bf16 v[92:95], v[162:165], v[194:197], v[92:95]
	v_mfma_f32_16x16x32_bf16 v[92:95], v[166:169], v[198:201], v[92:95]
	v_mfma_f32_16x16x32_bf16 v[76:79], v[162:165], v[202:205], v[76:79]
	v_mfma_f32_16x16x32_bf16 v[76:79], v[166:169], v[206:209], v[76:79]
	v_mfma_f32_16x16x32_bf16 v[68:71], v[170:173], v[202:205], v[68:71]
	v_mfma_f32_16x16x32_bf16 v[68:71], v[174:177], v[206:209], v[68:71]
	v_mfma_f32_16x16x32_bf16 v[84:87], v[170:173], v[194:197], v[84:87]
	v_mfma_f32_16x16x32_bf16 v[84:87], v[174:177], v[198:201], v[84:87]
	v_mfma_f32_16x16x32_bf16 v[100:103], v[170:173], v[186:189], v[100:103]
	v_mfma_f32_16x16x32_bf16 v[100:103], v[174:177], v[190:193], v[100:103]
	v_mfma_f32_16x16x32_bf16 v[116:119], v[170:173], v[178:181], v[116:119]
	v_mfma_f32_16x16x32_bf16 v[116:119], v[174:177], v[182:185], v[116:119]
	s_setprio 0
	s_barrier
	s_mov_b32 m0, s50
	v_lshl_add_u64 v[142:143], v[142:143], 0, s[64:65]
	s_add_u32 s18, s18, 0x80080
	ds_read_b128 v[178:181], v145 offset:49152
	ds_read_b128 v[182:185], v145 offset:50176
	ds_read_b128 v[186:189], v145 offset:51200
	ds_read_b128 v[190:193], v145 offset:52224
	ds_read_b128 v[194:197], v145 offset:53248
	ds_read_b128 v[198:201], v145 offset:54272
	ds_read_b128 v[202:205], v145 offset:55296
	ds_read_b128 v[206:209], v145 offset:56320
	global_load_lds_dwordx4 v[142:143], off
	v_lshl_add_u64 v[142:143], v[210:211], 0, s[64:65]
	s_mov_b32 m0, s51
	s_addc_u32 s19, s19, 0
	global_load_lds_dwordx4 v[142:143], off
	v_lshl_add_u64 v[142:143], s[18:19], 0, v[2:3]
	s_mov_b32 m0, s57
	s_nop 0
	global_load_lds_dwordx4 v[142:143], off
	v_lshl_add_u64 v[142:143], s[18:19], 0, v[132:133]
	s_mov_b32 m0, s58
	s_nop 0
	global_load_lds_dwordx4 v[142:143], off
	v_lshl_add_u64 v[142:143], v[212:213], 0, s[64:65]
	s_mov_b32 m0, s52
	s_nop 0
	global_load_lds_dwordx4 v[142:143], off
	v_lshl_add_u64 v[142:143], v[214:215], 0, s[64:65]
	s_mov_b32 m0, s53
	s_nop 0
	global_load_lds_dwordx4 v[142:143], off
	s_waitcnt vmcnt(8)
	s_waitcnt lgkmcnt(0)
	s_barrier
	s_setprio 1
	s_waitcnt lgkmcnt(0)
	v_mfma_f32_16x16x32_bf16 v[64:67], v[146:149], v[178:181], v[64:67]
	v_mfma_f32_16x16x32_bf16 v[64:67], v[150:153], v[182:185], v[64:67]
	v_mfma_f32_16x16x32_bf16 v[48:51], v[146:149], v[186:189], v[48:51]
	v_mfma_f32_16x16x32_bf16 v[48:51], v[150:153], v[190:193], v[48:51]
	v_mfma_f32_16x16x32_bf16 v[32:35], v[146:149], v[194:197], v[32:35]
	v_mfma_f32_16x16x32_bf16 v[32:35], v[150:153], v[198:201], v[32:35]
	v_mfma_f32_16x16x32_bf16 v[16:19], v[146:149], v[202:205], v[16:19]
	v_mfma_f32_16x16x32_bf16 v[16:19], v[150:153], v[206:209], v[16:19]
	v_mfma_f32_16x16x32_bf16 v[8:11], v[154:157], v[202:205], v[8:11]
	v_mfma_f32_16x16x32_bf16 v[8:11], v[158:161], v[206:209], v[8:11]
	v_mfma_f32_16x16x32_bf16 v[24:27], v[154:157], v[194:197], v[24:27]
	v_mfma_f32_16x16x32_bf16 v[24:27], v[158:161], v[198:201], v[24:27]
	v_mfma_f32_16x16x32_bf16 v[40:43], v[154:157], v[186:189], v[40:43]
	v_mfma_f32_16x16x32_bf16 v[40:43], v[158:161], v[190:193], v[40:43]
	v_mfma_f32_16x16x32_bf16 v[56:59], v[154:157], v[178:181], v[56:59]
	v_mfma_f32_16x16x32_bf16 v[56:59], v[158:161], v[182:185], v[56:59]
	s_setprio 0
	s_setprio 1
	v_mfma_f32_16x16x32_bf16 v[60:63], v[162:165], v[178:181], v[60:63]
	v_mfma_f32_16x16x32_bf16 v[60:63], v[166:169], v[182:185], v[60:63]
	v_mfma_f32_16x16x32_bf16 v[44:47], v[162:165], v[186:189], v[44:47]
	v_mfma_f32_16x16x32_bf16 v[44:47], v[166:169], v[190:193], v[44:47]
	v_mfma_f32_16x16x32_bf16 v[28:31], v[162:165], v[194:197], v[28:31]
	v_mfma_f32_16x16x32_bf16 v[28:31], v[166:169], v[198:201], v[28:31]
	v_mfma_f32_16x16x32_bf16 v[12:15], v[162:165], v[202:205], v[12:15]
	v_mfma_f32_16x16x32_bf16 v[12:15], v[166:169], v[206:209], v[12:15]
	s_add_i32 s74, s74, 2
	v_mfma_f32_16x16x32_bf16 v[4:7], v[170:173], v[202:205], v[4:7]
	v_mfma_f32_16x16x32_bf16 v[4:7], v[174:177], v[206:209], v[4:7]
	s_add_u32 s34, s34, 0x100
	s_addc_u32 s35, s35, 0
	v_mfma_f32_16x16x32_bf16 v[20:23], v[170:173], v[194:197], v[20:23]
	v_mfma_f32_16x16x32_bf16 v[20:23], v[174:177], v[198:201], v[20:23]
	s_add_u32 s71, s71, 0x100
	s_addc_u32 s73, s73, 0
	v_mfma_f32_16x16x32_bf16 v[36:39], v[170:173], v[186:189], v[36:39]
	v_mfma_f32_16x16x32_bf16 v[36:39], v[174:177], v[190:193], v[36:39]
	s_cmp_gt_u32 s74, 29
	v_mfma_f32_16x16x32_bf16 v[52:55], v[170:173], v[178:181], v[52:55]
	v_mfma_f32_16x16x32_bf16 v[52:55], v[174:177], v[182:185], v[52:55]
	s_setprio 0
	s_barrier
	s_cbranch_scc0 .LBB0_3116
	s_and_b64 vcc, exec, s[8:9]
	s_cbranch_vccz .LBB0_3119
	s_barrier

.LBB0_3195:
	v_add_u32_e32 v144, s26, v249
	v_add_u32_e32 v160, s38, v249
	ds_read_b128 v[132:135], v144
	ds_read_b128 v[136:139], v144 offset:1024
	ds_read_b128 v[140:143], v144 offset:2048
	ds_read_b128 v[144:147], v144 offset:3072
	ds_read_b128 v[148:151], v160
	ds_read_b128 v[152:155], v160 offset:1024
	ds_read_b128 v[156:159], v160 offset:2048
	ds_read_b128 v[160:163], v160 offset:3072
	s_add_u32 s24, s14, 0x100
	s_addc_u32 s25, s15, 0
	s_cmpk_eq_i32 s74, 0x54
	s_cselect_b32 s35, s5, s25
	s_cselect_b32 s34, s4, s24
	s_cselect_b32 s19, s13, s73
	s_cselect_b32 s18, s12, s71
	v_lshl_add_u64 v[196:197], s[14:15], 0, v[222:223]
	s_add_i32 m0, s41, 0xc000
	ds_read_b128 v[164:167], v250
	ds_read_b128 v[168:171], v250 offset:1024
	ds_read_b128 v[172:175], v250 offset:2048
	ds_read_b128 v[176:179], v250 offset:3072
	ds_read_b128 v[180:183], v250 offset:4096
	ds_read_b128 v[184:187], v250 offset:5120
	ds_read_b128 v[188:191], v250 offset:6144
	ds_read_b128 v[192:195], v250 offset:7168
	global_load_lds_dwordx4 v[196:197], off
	v_lshl_add_u64 v[196:197], s[14:15], 0, v[224:225]
	s_add_i32 m0, s41, 0xe000
	s_nop 0
	global_load_lds_dwordx4 v[196:197], off
	s_waitcnt vmcnt(8)
	s_waitcnt lgkmcnt(0)
	s_barrier
	s_setprio 1
	s_waitcnt lgkmcnt(0)
	v_mfma_f32_16x16x32_bf16 v[128:131], v[132:135], v[164:167], v[128:131]
	v_mfma_f32_16x16x32_bf16 v[128:131], v[136:139], v[168:171], v[128:131]
	v_mfma_f32_16x16x32_bf16 v[112:115], v[132:135], v[172:175], v[112:115]
	v_mfma_f32_16x16x32_bf16 v[112:115], v[136:139], v[176:179], v[112:115]
	v_mfma_f32_16x16x32_bf16 v[96:99], v[132:135], v[180:183], v[96:99]
	v_mfma_f32_16x16x32_bf16 v[96:99], v[136:139], v[184:187], v[96:99]
	v_mfma_f32_16x16x32_bf16 v[80:83], v[132:135], v[188:191], v[80:83]
	v_mfma_f32_16x16x32_bf16 v[80:83], v[136:139], v[192:195], v[80:83]
	v_mfma_f32_16x16x32_bf16 v[76:79], v[140:143], v[188:191], v[76:79]
	v_mfma_f32_16x16x32_bf16 v[76:79], v[144:147], v[192:195], v[76:79]
	v_mfma_f32_16x16x32_bf16 v[92:95], v[140:143], v[180:183], v[92:95]
	v_mfma_f32_16x16x32_bf16 v[92:95], v[144:147], v[184:187], v[92:95]
	v_mfma_f32_16x16x32_bf16 v[108:111], v[140:143], v[172:175], v[108:111]
	v_mfma_f32_16x16x32_bf16 v[108:111], v[144:147], v[176:179], v[108:111]
	v_mfma_f32_16x16x32_bf16 v[124:127], v[140:143], v[164:167], v[124:127]
	v_mfma_f32_16x16x32_bf16 v[124:127], v[144:147], v[168:171], v[124:127]
	s_setprio 0
	s_setprio 1
	v_mfma_f32_16x16x32_bf16 v[120:123], v[148:151], v[164:167], v[120:123]
	v_mfma_f32_16x16x32_bf16 v[120:123], v[152:155], v[168:171], v[120:123]
	v_mfma_f32_16x16x32_bf16 v[104:107], v[148:151], v[172:175], v[104:107]
	v_mfma_f32_16x16x32_bf16 v[104:107], v[152:155], v[176:179], v[104:107]
	v_mfma_f32_16x16x32_bf16 v[88:91], v[148:151], v[180:183], v[88:91]
	v_mfma_f32_16x16x32_bf16 v[88:91], v[152:155], v[184:187], v[88:91]
	v_mfma_f32_16x16x32_bf16 v[72:75], v[148:151], v[188:191], v[72:75]
	v_mfma_f32_16x16x32_bf16 v[72:75], v[152:155], v[192:195], v[72:75]
	v_mfma_f32_16x16x32_bf16 v[68:71], v[156:159], v[188:191], v[68:71]
	v_mfma_f32_16x16x32_bf16 v[68:71], v[160:163], v[192:195], v[68:71]
	v_mfma_f32_16x16x32_bf16 v[84:87], v[156:159], v[180:183], v[84:87]
	v_mfma_f32_16x16x32_bf16 v[84:87], v[160:163], v[184:187], v[84:87]
	v_mfma_f32_16x16x32_bf16 v[100:103], v[156:159], v[172:175], v[100:103]
	v_mfma_f32_16x16x32_bf16 v[100:103], v[160:163], v[176:179], v[100:103]
	v_mfma_f32_16x16x32_bf16 v[116:119], v[156:159], v[164:167], v[116:119]
	v_mfma_f32_16x16x32_bf16 v[116:119], v[160:163], v[168:171], v[116:119]
	s_setprio 0
	s_barrier
	s_mov_b32 m0, s27
	v_lshl_add_u64 v[196:197], s[18:19], 0, v[2:3]
	s_add_u32 s14, s18, 0x160000
	ds_read_b128 v[164:167], v250 offset:16384
	ds_read_b128 v[168:171], v250 offset:17408
	ds_read_b128 v[172:175], v250 offset:18432
	ds_read_b128 v[176:179], v250 offset:19456
	ds_read_b128 v[180:183], v250 offset:20480
	ds_read_b128 v[184:187], v250 offset:21504
	ds_read_b128 v[188:191], v250 offset:22528
	ds_read_b128 v[192:195], v250 offset:23552
	global_load_lds_dwordx4 v[196:197], off
	v_lshl_add_u64 v[198:199], s[18:19], 0, v[216:217]
	s_mov_b32 m0, s37
	s_addc_u32 s15, s19, 0
	global_load_lds_dwordx4 v[198:199], off
	v_lshl_add_u64 v[200:201], s[14:15], 0, v[2:3]
	s_mov_b32 m0, s39
	v_lshl_add_u64 v[202:203], s[34:35], 0, v[218:219]
	global_load_lds_dwordx4 v[200:201], off
	v_lshl_add_u64 v[200:201], s[14:15], 0, v[216:217]
	s_mov_b32 m0, s40
	s_nop 0
	global_load_lds_dwordx4 v[200:201], off
	v_lshl_add_u64 v[200:201], s[34:35], 0, v[220:221]
	s_mov_b32 m0, s41
	s_nop 0
	global_load_lds_dwordx4 v[200:201], off
	s_mov_b32 m0, s42
	s_nop 0
	global_load_lds_dwordx4 v[202:203], off
	s_waitcnt vmcnt(8)
	s_waitcnt lgkmcnt(0)
	s_barrier
	s_setprio 1
	s_waitcnt lgkmcnt(0)
	v_mfma_f32_16x16x32_bf16 v[64:67], v[132:135], v[164:167], v[64:67]
	v_mfma_f32_16x16x32_bf16 v[64:67], v[136:139], v[168:171], v[64:67]
	v_mfma_f32_16x16x32_bf16 v[48:51], v[132:135], v[172:175], v[48:51]
	v_mfma_f32_16x16x32_bf16 v[48:51], v[136:139], v[176:179], v[48:51]
	v_mfma_f32_16x16x32_bf16 v[32:35], v[132:135], v[180:183], v[32:35]
	v_mfma_f32_16x16x32_bf16 v[32:35], v[136:139], v[184:187], v[32:35]
	v_mfma_f32_16x16x32_bf16 v[16:19], v[132:135], v[188:191], v[16:19]
	v_mfma_f32_16x16x32_bf16 v[16:19], v[136:139], v[192:195], v[16:19]
	v_mfma_f32_16x16x32_bf16 v[12:15], v[140:143], v[188:191], v[12:15]
	v_mfma_f32_16x16x32_bf16 v[12:15], v[144:147], v[192:195], v[12:15]
	v_mfma_f32_16x16x32_bf16 v[28:31], v[140:143], v[180:183], v[28:31]
	v_mfma_f32_16x16x32_bf16 v[28:31], v[144:147], v[184:187], v[28:31]
	v_mfma_f32_16x16x32_bf16 v[44:47], v[140:143], v[172:175], v[44:47]
	v_mfma_f32_16x16x32_bf16 v[44:47], v[144:147], v[176:179], v[44:47]
	v_mfma_f32_16x16x32_bf16 v[60:63], v[140:143], v[164:167], v[60:63]
	v_mfma_f32_16x16x32_bf16 v[60:63], v[144:147], v[168:171], v[60:63]
	s_setprio 0
	s_setprio 1
	v_mfma_f32_16x16x32_bf16 v[56:59], v[148:151], v[164:167], v[56:59]
	v_mfma_f32_16x16x32_bf16 v[56:59], v[152:155], v[168:171], v[56:59]
	v_mfma_f32_16x16x32_bf16 v[40:43], v[148:151], v[172:175], v[40:43]
	v_mfma_f32_16x16x32_bf16 v[40:43], v[152:155], v[176:179], v[40:43]
	v_mfma_f32_16x16x32_bf16 v[24:27], v[148:151], v[180:183], v[24:27]
	v_mfma_f32_16x16x32_bf16 v[24:27], v[152:155], v[184:187], v[24:27]
	v_mfma_f32_16x16x32_bf16 v[8:11], v[148:151], v[188:191], v[8:11]
	v_mfma_f32_16x16x32_bf16 v[8:11], v[152:155], v[192:195], v[8:11]
	v_mfma_f32_16x16x32_bf16 v[4:7], v[156:159], v[188:191], v[4:7]
	v_mfma_f32_16x16x32_bf16 v[4:7], v[160:163], v[192:195], v[4:7]
	v_mfma_f32_16x16x32_bf16 v[20:23], v[156:159], v[180:183], v[20:23]
	v_mfma_f32_16x16x32_bf16 v[20:23], v[160:163], v[184:187], v[20:23]
	v_mfma_f32_16x16x32_bf16 v[36:39], v[156:159], v[172:175], v[36:39]
	v_mfma_f32_16x16x32_bf16 v[36:39], v[160:163], v[176:179], v[36:39]
	v_mfma_f32_16x16x32_bf16 v[52:55], v[156:159], v[164:167], v[52:55]
	v_mfma_f32_16x16x32_bf16 v[52:55], v[160:163], v[168:171], v[52:55]
	s_setprio 0
	s_barrier
	v_add_u32_e32 v144, s49, v249
	v_add_u32_e32 v160, s56, v249
	ds_read_b128 v[132:135], v144
	ds_read_b128 v[136:139], v144 offset:1024
	ds_read_b128 v[140:143], v144 offset:2048
	ds_read_b128 v[144:147], v144 offset:3072
	ds_read_b128 v[148:151], v160
	ds_read_b128 v[152:155], v160 offset:1024
	ds_read_b128 v[156:159], v160 offset:2048
	ds_read_b128 v[160:163], v160 offset:3072
	s_add_u32 s14, s34, 0x160000
	s_addc_u32 s15, s35, 0
	s_mov_b32 m0, s43
	v_lshl_add_u64 v[204:205], s[14:15], 0, v[220:221]
	ds_read_b128 v[164:167], v250 offset:32768
	ds_read_b128 v[168:171], v250 offset:33792
	ds_read_b128 v[172:175], v250 offset:34816
	ds_read_b128 v[176:179], v250 offset:35840
	ds_read_b128 v[180:183], v250 offset:36864
	ds_read_b128 v[184:187], v250 offset:37888
	ds_read_b128 v[188:191], v250 offset:38912
	ds_read_b128 v[192:195], v250 offset:39936
	global_load_lds_dwordx4 v[204:205], off
	v_lshl_add_u64 v[204:205], s[14:15], 0, v[218:219]
	s_mov_b32 m0, s44
	s_nop 0
	global_load_lds_dwordx4 v[204:205], off
	s_waitcnt vmcnt(8)
	s_waitcnt lgkmcnt(0)
	s_barrier
	s_setprio 1
	s_waitcnt lgkmcnt(0)
	v_mfma_f32_16x16x32_bf16 v[128:131], v[132:135], v[164:167], v[128:131]
	v_mfma_f32_16x16x32_bf16 v[128:131], v[136:139], v[168:171], v[128:131]
	v_mfma_f32_16x16x32_bf16 v[112:115], v[132:135], v[172:175], v[112:115]
	v_mfma_f32_16x16x32_bf16 v[112:115], v[136:139], v[176:179], v[112:115]
	v_mfma_f32_16x16x32_bf16 v[96:99], v[132:135], v[180:183], v[96:99]
	v_mfma_f32_16x16x32_bf16 v[96:99], v[136:139], v[184:187], v[96:99]
	v_mfma_f32_16x16x32_bf16 v[80:83], v[132:135], v[188:191], v[80:83]
	v_mfma_f32_16x16x32_bf16 v[80:83], v[136:139], v[192:195], v[80:83]
	v_mfma_f32_16x16x32_bf16 v[76:79], v[140:143], v[188:191], v[76:79]
	v_mfma_f32_16x16x32_bf16 v[76:79], v[144:147], v[192:195], v[76:79]
	v_mfma_f32_16x16x32_bf16 v[92:95], v[140:143], v[180:183], v[92:95]
	v_mfma_f32_16x16x32_bf16 v[92:95], v[144:147], v[184:187], v[92:95]
	v_mfma_f32_16x16x32_bf16 v[108:111], v[140:143], v[172:175], v[108:111]
	v_mfma_f32_16x16x32_bf16 v[108:111], v[144:147], v[176:179], v[108:111]
	v_mfma_f32_16x16x32_bf16 v[124:127], v[140:143], v[164:167], v[124:127]
	v_mfma_f32_16x16x32_bf16 v[124:127], v[144:147], v[168:171], v[124:127]
	s_setprio 0
	s_setprio 1
	v_mfma_f32_16x16x32_bf16 v[120:123], v[148:151], v[164:167], v[120:123]
	v_mfma_f32_16x16x32_bf16 v[120:123], v[152:155], v[168:171], v[120:123]
	v_mfma_f32_16x16x32_bf16 v[104:107], v[148:151], v[172:175], v[104:107]
	v_mfma_f32_16x16x32_bf16 v[104:107], v[152:155], v[176:179], v[104:107]
	v_mfma_f32_16x16x32_bf16 v[88:91], v[148:151], v[180:183], v[88:91]
	v_mfma_f32_16x16x32_bf16 v[88:91], v[152:155], v[184:187], v[88:91]
	v_mfma_f32_16x16x32_bf16 v[72:75], v[148:151], v[188:191], v[72:75]
	v_mfma_f32_16x16x32_bf16 v[72:75], v[152:155], v[192:195], v[72:75]
	v_mfma_f32_16x16x32_bf16 v[68:71], v[156:159], v[188:191], v[68:71]
	v_mfma_f32_16x16x32_bf16 v[68:71], v[160:163], v[192:195], v[68:71]
	v_mfma_f32_16x16x32_bf16 v[84:87], v[156:159], v[180:183], v[84:87]
	v_mfma_f32_16x16x32_bf16 v[84:87], v[160:163], v[184:187], v[84:87]
	v_mfma_f32_16x16x32_bf16 v[100:103], v[156:159], v[172:175], v[100:103]
	v_mfma_f32_16x16x32_bf16 v[100:103], v[160:163], v[176:179], v[100:103]
	v_mfma_f32_16x16x32_bf16 v[116:119], v[156:159], v[164:167], v[116:119]
	v_mfma_f32_16x16x32_bf16 v[116:119], v[160:163], v[168:171], v[116:119]
	s_setprio 0
	s_barrier
	s_mov_b32 m0, s50
	v_lshl_add_u64 v[196:197], v[196:197], 0, s[64:65]
	s_add_u32 s14, s18, 0x160080
	ds_read_b128 v[164:167], v250 offset:49152
	ds_read_b128 v[168:171], v250 offset:50176
	ds_read_b128 v[172:175], v250 offset:51200
	ds_read_b128 v[176:179], v250 offset:52224
	ds_read_b128 v[180:183], v250 offset:53248
	ds_read_b128 v[184:187], v250 offset:54272
	ds_read_b128 v[188:191], v250 offset:55296
	ds_read_b128 v[192:195], v250 offset:56320
	global_load_lds_dwordx4 v[196:197], off
	v_lshl_add_u64 v[196:197], v[198:199], 0, s[64:65]
	s_mov_b32 m0, s51
	s_addc_u32 s15, s19, 0
	global_load_lds_dwordx4 v[196:197], off
	v_lshl_add_u64 v[196:197], s[14:15], 0, v[2:3]
	s_mov_b32 m0, s57
	s_nop 0
	global_load_lds_dwordx4 v[196:197], off
	v_lshl_add_u64 v[196:197], s[14:15], 0, v[216:217]
	s_mov_b32 m0, s58
	s_nop 0
	global_load_lds_dwordx4 v[196:197], off
	v_lshl_add_u64 v[196:197], v[200:201], 0, s[64:65]
	s_mov_b32 m0, s52
	s_nop 0
	global_load_lds_dwordx4 v[196:197], off
	v_lshl_add_u64 v[196:197], v[202:203], 0, s[64:65]
	s_mov_b32 m0, s53
	s_nop 0
	global_load_lds_dwordx4 v[196:197], off
	s_waitcnt vmcnt(8)
	s_waitcnt lgkmcnt(0)
	s_barrier
	s_setprio 1
	s_waitcnt lgkmcnt(0)
	v_mfma_f32_16x16x32_bf16 v[64:67], v[132:135], v[164:167], v[64:67]
	v_mfma_f32_16x16x32_bf16 v[64:67], v[136:139], v[168:171], v[64:67]
	v_mfma_f32_16x16x32_bf16 v[48:51], v[132:135], v[172:175], v[48:51]
	v_mfma_f32_16x16x32_bf16 v[48:51], v[136:139], v[176:179], v[48:51]
	v_mfma_f32_16x16x32_bf16 v[32:35], v[132:135], v[180:183], v[32:35]
	v_mfma_f32_16x16x32_bf16 v[32:35], v[136:139], v[184:187], v[32:35]
	v_mfma_f32_16x16x32_bf16 v[16:19], v[132:135], v[188:191], v[16:19]
	v_mfma_f32_16x16x32_bf16 v[16:19], v[136:139], v[192:195], v[16:19]
	v_mfma_f32_16x16x32_bf16 v[12:15], v[140:143], v[188:191], v[12:15]
	v_mfma_f32_16x16x32_bf16 v[12:15], v[144:147], v[192:195], v[12:15]
	v_mfma_f32_16x16x32_bf16 v[28:31], v[140:143], v[180:183], v[28:31]
	v_mfma_f32_16x16x32_bf16 v[28:31], v[144:147], v[184:187], v[28:31]
	v_mfma_f32_16x16x32_bf16 v[44:47], v[140:143], v[172:175], v[44:47]
	v_mfma_f32_16x16x32_bf16 v[44:47], v[144:147], v[176:179], v[44:47]
	v_mfma_f32_16x16x32_bf16 v[60:63], v[140:143], v[164:167], v[60:63]
	v_mfma_f32_16x16x32_bf16 v[60:63], v[144:147], v[168:171], v[60:63]
	s_setprio 0
	s_setprio 1
	v_mfma_f32_16x16x32_bf16 v[56:59], v[148:151], v[164:167], v[56:59]
	v_mfma_f32_16x16x32_bf16 v[56:59], v[152:155], v[168:171], v[56:59]
	v_mfma_f32_16x16x32_bf16 v[40:43], v[148:151], v[172:175], v[40:43]
	v_mfma_f32_16x16x32_bf16 v[40:43], v[152:155], v[176:179], v[40:43]
	v_mfma_f32_16x16x32_bf16 v[24:27], v[148:151], v[180:183], v[24:27]
	v_mfma_f32_16x16x32_bf16 v[24:27], v[152:155], v[184:187], v[24:27]
	v_mfma_f32_16x16x32_bf16 v[8:11], v[148:151], v[188:191], v[8:11]
	v_mfma_f32_16x16x32_bf16 v[8:11], v[152:155], v[192:195], v[8:11]
	s_add_i32 s74, s74, 2
	v_mfma_f32_16x16x32_bf16 v[4:7], v[156:159], v[188:191], v[4:7]
	v_mfma_f32_16x16x32_bf16 v[4:7], v[160:163], v[192:195], v[4:7]
	s_add_u32 s71, s71, 0x100
	s_addc_u32 s73, s73, 0
	v_mfma_f32_16x16x32_bf16 v[20:23], v[156:159], v[180:183], v[20:23]
	v_mfma_f32_16x16x32_bf16 v[20:23], v[160:163], v[184:187], v[20:23]
	s_cmpk_gt_u32 s74, 0x55
	v_mfma_f32_16x16x32_bf16 v[36:39], v[156:159], v[172:175], v[36:39]
	v_mfma_f32_16x16x32_bf16 v[36:39], v[160:163], v[176:179], v[36:39]
	v_mfma_f32_16x16x32_bf16 v[52:55], v[156:159], v[164:167], v[52:55]
	v_mfma_f32_16x16x32_bf16 v[52:55], v[160:163], v[168:171], v[52:55]
	s_setprio 0
	s_barrier
	s_mov_b64 s[14:15], s[24:25]
	s_cbranch_scc0 .LBB0_3195
	s_and_b64 vcc, exec, s[10:11]
	s_cbranch_vccz .LBB0_3198
	s_barrier
